# workgroup dequeue takes 16 items (two consecutive key blocks) per atomic: one barrier per two blocks
# baseline (speedup 1.0000x reference)
; __device__ __forceinline__ void sb_decode_stream(Frame& F, unsigned* qctr, int base, int limit) {
;     const float* CK = kin(2); const float* CV = kin(3); const int* PT = (const int*)kin(4);
;     int lane = F.lane; asm volatile("" : "+v"(lane));
;     const int half = lane >> 5, l32 = lane & 31;
;     const float k1 = SB_SCALE * 1.4426950408889634f;
;     const size_t lo = (size_t)half * (NH * HD) + 4 * l32;
;     int it;
;     { const unsigned v = __hip_atomic_fetch_add(qctr, 1u, __ATOMIC_RELAXED, __HIP_MEMORY_SCOPE_AGENT);
;       it = (int)(__builtin_amdgcn_readfirstlane(v) >> 6); if (it >= limit) return; it += base; }
; __global__ void __launch_bounds__(NWAVES * 64, 2) hymba_fwd(Args args) {
;     ...
;         const bool streamer = (F.bid % 3) == 0 && F.bid < 252;
;         if (streamer) sb_decode_stream(F, F.ctl + CW_QUEUE, 0, DEC_Q2);
.LBB0_1119:
	s_cmp_lt_i32 s84, 3
	s_cselect_b64 s[2:3], -1, 0
	s_cmp_gt_i32 s85, 2
	s_cselect_b64 s[4:5], -1, 0
	s_and_b64 s[2:3], s[2:3], s[4:5]
	s_andn2_b64 vcc, exec, s[2:3]
	s_cbranch_vccnz .LBB0_1376
	s_lshr_b32 s2, s96, 3
	s_mov_b32 s3, 0x4a5294a5
	s_lshr_b32 s3, s3, s2
	s_and_b32 s3, s3, 1
	s_cmp_eq_u32 s3, 1
	s_cselect_b64 s[42:43], -1, 0
	s_add_u32 s40, s26, 0x1000
	s_addc_u32 s41, s27, 0
	s_add_u32 s38, s26, 0x2ff18000
	s_addc_u32 s39, s27, 0
	s_add_u32 s3, s26, 0x2ff70400
	s_addc_u32 s4, s27, 0
	s_and_b64 vcc, exec, s[42:43]
	s_cbranch_vccz .LBB0_1132
	s_load_dwordx2 s[50:51], s[0:1], 0x10
	s_load_dwordx2 s[52:53], s[0:1], 0x18
	s_load_dwordx2 s[54:55], s[0:1], 0x20
	s_load_dwordx2 s[56:57], s[0:1], 0x60
	s_add_u32 s58, s26, 0x1000
	s_addc_u32 s59, s27, 0
	s_add_u32 s60, s26, 0x2ff18000
	s_addc_u32 s61, s27, 0
	s_add_u32 s62, s26, 0x2ff70400
	s_addc_u32 s63, s27, 0
	s_mov_b32 s76, 0xcccccccc
	s_mov_b32 s77, 0xcccccccc
	s_mov_b32 s78, 0xaaaaaaaa
	s_mov_b32 s79, 0xaaaaaaaa
	v_and_b32_e32 v193, 31, v199
	v_lshrrev_b32_e32 v188, 5, v199
	v_lshlrev_b32_e32 v193, 4, v193
	v_lshl_add_u32 v187, v188, 12, v193
	v_lshlrev_b32_e32 v188, 7, v188
	v_mov_b32_e32 v189, 0
	v_mov_b32_e32 v190, 64
	v_mov_b32_e32 v190, 0x400
	s_mov_b32 s37, 0x251e0
	s_cmp_eq_u32 s94, 0
	s_cbranch_scc0 .Ldqa_pro
	s_mov_b64 exec, 1
	global_atomic_add v191, v189, v190, s[58:59] sc0
	s_mov_b64 exec, -1

; __device__ __forceinline__ void sb_decode_stream(Frame& F, unsigned* qctr, int base, int limit) {
;     const float* CK = kin(2); const float* CV = kin(3); const int* PT = (const int*)kin(4);
;     int lane = F.lane; asm volatile("" : "+v"(lane));
;     const int half = lane >> 5, l32 = lane & 31;
;     const float k1 = SB_SCALE * 1.4426950408889634f;
;     const size_t lo = (size_t)half * (NH * HD) + 4 * l32;
;     int it;
;     { const unsigned v = __hip_atomic_fetch_add(qctr, 1u, __ATOMIC_RELAXED, __HIP_MEMORY_SCOPE_AGENT);
;       it = (int)(__builtin_amdgcn_readfirstlane(v) >> 6); if (it >= limit) return; it += base; }
;     f32x4 A[16], B[16], q4;
;     size_t cb;
;     { const int b = it >> 11, h = it & 7, p0 = ((it >> 3) & 255) * 64;
;       const int page = PT[b * NPAGES + (p0 >> 7)];
;       cb = (((size_t)page * PAGE + (p0 & 127)) * NH + h) * HD + lo;
;       q4 = *(const f32x4*)(SSP(S_PROJ) + (size_t)b * IN_COLS + h * HD + 4 * l32);
; #pragma unroll
;       for (int i = 0; i < 16; ++i) A[i] = __builtin_nontemporal_load((const f32x4*)(CK + cb + (size_t)(2 * i) * (NH * HD)));
; #pragma unroll
;       for (int i = 0; i < 16; ++i) B[i] = __builtin_nontemporal_load((const f32x4*)(CK + cb + (size_t)(32 + 2 * i) * (NH * HD))); }
.Ldqa_sh1:
	s_barrier
	ds_read_b32 v201, v200
	s_xor_b32 s37, s37, 4
	s_waitcnt lgkmcnt(0)
	v_readfirstlane_b32 s2, v201
	s_nop 0
	s_lshr_b32 s72, s2, 6
	s_cmp_ge_u32 s72, 0x1800
	s_cbranch_scc1 .Ldqa_exit
	s_mov_b32 s74, s72
	s_add_u32 s72, s72, s94
	s_min_u32 s72, s72, 0x17ff
	s_mov_b32 s75, 1
	s_waitcnt lgkmcnt(0)
	s_lshr_b32 s6, s72, 11
	s_and_b32 s7, s72, 7
	s_bfe_u32 s8, s72, 0x80003
	s_lshl_b32 s9, s6, 7
	s_lshr_b32 s10, s8, 1
	s_or_b32 s9, s9, s10
	s_lshl_b32 s9, s9, 2
	s_lshl_b32 s10, s7, 2
	s_load_dword s29, s[54:55], s9
	s_load_dword s30, s[56:57], s10
	s_waitcnt lgkmcnt(0)
	s_mov_b32 s12, s29
	s_mov_b32 s13, 0
	s_lshl_b64 s[12:13], s[12:13], 19
	s_and_b32 s14, s8, 1
	s_lshl_b32 s14, s14, 18
	s_lshl_b32 s15, s7, 9
	s_or_b32 s14, s14, s15
	s_or_b32 s80, s12, s14
	s_mov_b32 s81, s13
	s_add_u32 s64, s50, s80
	s_addc_u32 s65, s51, s81
	s_mul_i32 s16, s6, 0x7040
	s_add_u32 s16, s16, s15
	s_add_u32 s16, s60, s16
	s_addc_u32 s17, s61, 0
	global_load_dwordx4 v[156:159], v193, s[16:17]
	global_load_dwordx4 v[4:7], v187, s[64:65] nt
	s_add_u32 s64, s64, 0x2000
	s_addc_u32 s65, s65, 0
	global_load_dwordx4 v[8:11], v187, s[64:65] nt
	s_add_u32 s64, s64, 0x2000
	s_addc_u32 s65, s65, 0
	global_load_dwordx4 v[12:15], v187, s[64:65] nt
	s_add_u32 s64, s64, 0x2000
	s_addc_u32 s65, s65, 0
	global_load_dwordx4 v[16:19], v187, s[64:65] nt
	s_add_u32 s64, s64, 0x2000
	s_addc_u32 s65, s65, 0
	global_load_dwordx4 v[20:23], v187, s[64:65] nt
	s_add_u32 s64, s64, 0x2000
	s_addc_u32 s65, s65, 0
	global_load_dwordx4 v[24:27], v187, s[64:65] nt
	s_add_u32 s64, s64, 0x2000
	s_addc_u32 s65, s65, 0
	global_load_dwordx4 v[28:31], v187, s[64:65] nt
	s_add_u32 s64, s64, 0x2000
	s_addc_u32 s65, s65, 0
	global_load_dwordx4 v[32:35], v187, s[64:65] nt
	s_add_u32 s64, s64, 0x2000
	s_addc_u32 s65, s65, 0
	global_load_dwordx4 v[36:39], v187, s[64:65] nt
	s_add_u32 s64, s64, 0x2000
	s_addc_u32 s65, s65, 0
	global_load_dwordx4 v[40:43], v187, s[64:65] nt
	s_add_u32 s64, s64, 0x2000
	s_addc_u32 s65, s65, 0
	global_load_dwordx4 v[44:47], v187, s[64:65] nt
	s_add_u32 s64, s64, 0x2000
	s_addc_u32 s65, s65, 0
	global_load_dwordx4 v[48:51], v187, s[64:65] nt
	s_add_u32 s64, s64, 0x2000
	s_addc_u32 s65, s65, 0
	global_load_dwordx4 v[52:55], v187, s[64:65] nt
	s_add_u32 s64, s64, 0x2000
	s_addc_u32 s65, s65, 0
	global_load_dwordx4 v[56:59], v187, s[64:65] nt
	s_add_u32 s64, s64, 0x2000
	s_addc_u32 s65, s65, 0
	global_load_dwordx4 v[60:63], v187, s[64:65] nt
	s_add_u32 s64, s64, 0x2000
	s_addc_u32 s65, s65, 0
	global_load_dwordx4 v[64:67], v187, s[64:65] nt
	s_add_u32 s64, s64, 0x2000
	s_addc_u32 s65, s65, 0
	global_load_dwordx4 v[68:71], v187, s[64:65] nt
	s_add_u32 s64, s64, 0x2000
	s_addc_u32 s65, s65, 0
	global_load_dwordx4 v[72:75], v187, s[64:65] nt
	s_add_u32 s64, s64, 0x2000
	s_addc_u32 s65, s65, 0
	global_load_dwordx4 v[76:79], v187, s[64:65] nt
	s_add_u32 s64, s64, 0x2000
	s_addc_u32 s65, s65, 0
	global_load_dwordx4 v[80:83], v187, s[64:65] nt
	s_add_u32 s64, s64, 0x2000
	s_addc_u32 s65, s65, 0
	global_load_dwordx4 v[84:87], v187, s[64:65] nt
	s_add_u32 s64, s64, 0x2000
	s_addc_u32 s65, s65, 0
	global_load_dwordx4 v[88:91], v187, s[64:65] nt
	s_add_u32 s64, s64, 0x2000
	s_addc_u32 s65, s65, 0
	global_load_dwordx4 v[92:95], v187, s[64:65] nt
	s_add_u32 s64, s64, 0x2000
	s_addc_u32 s65, s65, 0
	global_load_dwordx4 v[96:99], v187, s[64:65] nt
	s_add_u32 s64, s64, 0x2000
	s_addc_u32 s65, s65, 0
	global_load_dwordx4 v[100:103], v187, s[64:65] nt
	s_add_u32 s64, s64, 0x2000
	s_addc_u32 s65, s65, 0
	global_load_dwordx4 v[104:107], v187, s[64:65] nt
	s_add_u32 s64, s64, 0x2000
	s_addc_u32 s65, s65, 0
	global_load_dwordx4 v[108:111], v187, s[64:65] nt
	s_add_u32 s64, s64, 0x2000
	s_addc_u32 s65, s65, 0
	global_load_dwordx4 v[112:115], v187, s[64:65] nt
	s_add_u32 s64, s64, 0x2000
	s_addc_u32 s65, s65, 0
	global_load_dwordx4 v[116:119], v187, s[64:65] nt
	s_add_u32 s64, s64, 0x2000
	s_addc_u32 s65, s65, 0
	global_load_dwordx4 v[120:123], v187, s[64:65] nt
	s_add_u32 s64, s64, 0x2000
	s_addc_u32 s65, s65, 0
	global_load_dwordx4 v[124:127], v187, s[64:65] nt
	s_add_u32 s64, s64, 0x2000
	s_addc_u32 s65, s65, 0
	global_load_dwordx4 v[128:131], v187, s[64:65] nt
	s_add_u32 s64, s64, 0x2000
	s_addc_u32 s65, s65, 0
	global_load_dword v194, v189, s[58:59]
	global_load_dword v195, v189, s[58:59]
.Ldqa_loop:
	s_nop 0
	s_mov_b32 s28, s30
	s_mov_b32 s68, s80
	s_mov_b32 s69, s81
	s_mov_b32 s35, 0
	s_cmp_eq_u32 s75, 0
	s_cselect_b32 s35, 1, 0
	s_cselect_b32 s75, s75, 0
	s_cmp_eq_u32 s35, 1
	s_cbranch_scc0 .Ldqa_fetch
	s_cmp_eq_u32 s94, 0
	s_cbranch_scc0 .Ldqa_fetch
	s_mov_b64 exec, 1
	global_atomic_add v191, v189, v190, s[58:59] sc0
	s_mov_b64 exec, -1
	s_branch .Ldqa_fetched

; __device__ __forceinline__ void sb_decode_stream(Frame& F, unsigned* qctr, int base, int limit) {
;     ...
;         const int bh = ((it >> 11) << 3) | (it & 7), blk = (it >> 3) & 255, h = it & 7;
;         const unsigned vn = __hip_atomic_fetch_add(qctr, 1u, __ATOMIC_RELAXED, __HIP_MEMORY_SCOPE_AGENT);
;         const float k2 = kin(12)[h] * 1.4426950408889634f;
;         int zi = 0;
;     ...
;         DEC_SCORES(A, 0);
; #pragma unroll
;         for (int i = 0; i < 16; ++i) A[i] = __builtin_nontemporal_load((const f32x4*)(CV + cb + (size_t)(2 * i) * (NH * HD)));
.Ldqa_fetched:
	s_nop 0
	s_add_u32 s66, s52, s68
	s_addc_u32 s67, s53, s69
	s_lshr_b32 s18, s72, 11
	s_lshl_b32 s18, s18, 3
	s_and_b32 s19, s72, 7
	s_or_b32 s18, s18, s19
	s_lshl_b32 s18, s18, 8
	s_bfe_u32 s19, s72, 0x80003
	s_or_b32 s18, s18, s19
	s_mul_i32 s18, s18, 0x210
	s_add_u32 s70, s62, s18
	s_addc_u32 s71, s63, 0
	v_mov_b32_e32 v192, s28
	v_mul_f32_e32 v192, 0x3fb8aa3b, v192
	s_waitcnt vmcnt(34)
	v_mov_b32_e32 v152, v156
	v_mov_b32_e32 v153, v157
	v_mov_b32_e32 v154, v158
	v_mov_b32_e32 v155, v159
	v_pk_mul_f32 v[148:149], v[4:5], v[152:153]
	v_pk_fma_f32 v[148:149], v[6:7], v[154:155], v[148:149]
	global_load_dwordx4 v[4:7], v187, s[66:67] nt
	s_add_u32 s66, s66, 0x2000
	s_addc_u32 s67, s67, 0
	v_add_f32_e32 v132, v148, v149
	s_waitcnt vmcnt(34)
	v_pk_mul_f32 v[150:151], v[8:9], v[152:153]
	v_pk_fma_f32 v[150:151], v[10:11], v[154:155], v[150:151]
	global_load_dwordx4 v[8:11], v187, s[66:67] nt
	s_add_u32 s66, s66, 0x2000
	s_addc_u32 s67, s67, 0
	v_add_f32_e32 v133, v150, v151
	s_waitcnt vmcnt(34)
	v_pk_mul_f32 v[148:149], v[12:13], v[152:153]
	v_pk_fma_f32 v[148:149], v[14:15], v[154:155], v[148:149]
	global_load_dwordx4 v[12:15], v187, s[66:67] nt
	s_add_u32 s66, s66, 0x2000
	s_addc_u32 s67, s67, 0
	v_add_f32_e32 v134, v148, v149
	s_waitcnt vmcnt(34)
	v_pk_mul_f32 v[150:151], v[16:17], v[152:153]
	v_pk_fma_f32 v[150:151], v[18:19], v[154:155], v[150:151]
	global_load_dwordx4 v[16:19], v187, s[66:67] nt
	s_add_u32 s66, s66, 0x2000
	s_addc_u32 s67, s67, 0
	v_add_f32_e32 v135, v150, v151
	s_waitcnt vmcnt(34)
	v_pk_mul_f32 v[148:149], v[20:21], v[152:153]
	v_pk_fma_f32 v[148:149], v[22:23], v[154:155], v[148:149]
	global_load_dwordx4 v[20:23], v187, s[66:67] nt
	s_add_u32 s66, s66, 0x2000
	s_addc_u32 s67, s67, 0
	v_add_f32_e32 v136, v148, v149
	s_waitcnt vmcnt(34)
	v_pk_mul_f32 v[150:151], v[24:25], v[152:153]
	v_pk_fma_f32 v[150:151], v[26:27], v[154:155], v[150:151]
	global_load_dwordx4 v[24:27], v187, s[66:67] nt
	s_add_u32 s66, s66, 0x2000
	s_addc_u32 s67, s67, 0
	v_add_f32_e32 v137, v150, v151
	s_waitcnt vmcnt(34)
	v_pk_mul_f32 v[148:149], v[28:29], v[152:153]
	v_pk_fma_f32 v[148:149], v[30:31], v[154:155], v[148:149]
	global_load_dwordx4 v[28:31], v187, s[66:67] nt
	s_add_u32 s66, s66, 0x2000
	s_addc_u32 s67, s67, 0
	v_add_f32_e32 v138, v148, v149
	s_waitcnt vmcnt(34)
	v_pk_mul_f32 v[150:151], v[32:33], v[152:153]
	v_pk_fma_f32 v[150:151], v[34:35], v[154:155], v[150:151]
	global_load_dwordx4 v[32:35], v187, s[66:67] nt
	s_add_u32 s66, s66, 0x2000
	s_addc_u32 s67, s67, 0
	v_add_f32_e32 v139, v150, v151
	s_waitcnt vmcnt(34)
	v_pk_mul_f32 v[148:149], v[36:37], v[152:153]
	v_pk_fma_f32 v[148:149], v[38:39], v[154:155], v[148:149]
	global_load_dwordx4 v[36:39], v187, s[66:67] nt
	s_add_u32 s66, s66, 0x2000
	s_addc_u32 s67, s67, 0
	v_add_f32_e32 v140, v148, v149
	s_waitcnt vmcnt(34)
	v_pk_mul_f32 v[150:151], v[40:41], v[152:153]
	v_pk_fma_f32 v[150:151], v[42:43], v[154:155], v[150:151]
	global_load_dwordx4 v[40:43], v187, s[66:67] nt
	s_add_u32 s66, s66, 0x2000
	s_addc_u32 s67, s67, 0
	v_add_f32_e32 v141, v150, v151
	s_waitcnt vmcnt(34)
	v_pk_mul_f32 v[148:149], v[44:45], v[152:153]
	v_pk_fma_f32 v[148:149], v[46:47], v[154:155], v[148:149]
	global_load_dwordx4 v[44:47], v187, s[66:67] nt
	s_add_u32 s66, s66, 0x2000
	s_addc_u32 s67, s67, 0
	v_add_f32_e32 v142, v148, v149
	s_waitcnt vmcnt(34)
	v_pk_mul_f32 v[150:151], v[48:49], v[152:153]
	v_pk_fma_f32 v[150:151], v[50:51], v[154:155], v[150:151]
	global_load_dwordx4 v[48:51], v187, s[66:67] nt
	s_add_u32 s66, s66, 0x2000
	s_addc_u32 s67, s67, 0
	v_add_f32_e32 v143, v150, v151
	s_waitcnt vmcnt(34)
	v_pk_mul_f32 v[148:149], v[52:53], v[152:153]
	v_pk_fma_f32 v[148:149], v[54:55], v[154:155], v[148:149]
	global_load_dwordx4 v[52:55], v187, s[66:67] nt
	s_add_u32 s66, s66, 0x2000
	s_addc_u32 s67, s67, 0
	v_add_f32_e32 v144, v148, v149
	s_waitcnt vmcnt(34)
	v_pk_mul_f32 v[150:151], v[56:57], v[152:153]
	v_pk_fma_f32 v[150:151], v[58:59], v[154:155], v[150:151]
	global_load_dwordx4 v[56:59], v187, s[66:67] nt
	s_add_u32 s66, s66, 0x2000
	s_addc_u32 s67, s67, 0
	v_add_f32_e32 v145, v150, v151
	s_waitcnt vmcnt(34)
	v_pk_mul_f32 v[148:149], v[60:61], v[152:153]
	v_pk_fma_f32 v[148:149], v[62:63], v[154:155], v[148:149]
	global_load_dwordx4 v[60:63], v187, s[66:67] nt
	s_add_u32 s66, s66, 0x2000
	s_addc_u32 s67, s67, 0
	v_add_f32_e32 v146, v148, v149
	s_waitcnt vmcnt(34)
; __device__ __forceinline__ void sb_decode_stream(Frame& F, unsigned* qctr, int base, int limit) {
;     ...
;         DEC_SCORES(A, 0);
; #pragma unroll
;         for (int i = 0; i < 16; ++i) A[i] = __builtin_nontemporal_load((const f32x4*)(CV + cb + (size_t)(2 * i) * (NH * HD)));
;         DEC_SCORES(B, 1);
;     ...
; #pragma unroll
;         for (int i = 0; i < 16; ++i) B[i] = __builtin_nontemporal_load((const f32x4*)(CV + cb + (size_t)(32 + 2 * i) * (NH * HD)));
;     ...
;         int itn = (int)(__builtin_amdgcn_readfirstlane(vn) >> 6); const bool more = itn < limit; itn = more ? itn + base : it;
	v_pk_mul_f32 v[150:151], v[64:65], v[152:153]
	v_pk_fma_f32 v[150:151], v[66:67], v[154:155], v[150:151]
	global_load_dwordx4 v[64:67], v187, s[66:67] nt
	s_add_u32 s66, s66, 0x2000
	s_addc_u32 s67, s67, 0
	v_add_f32_e32 v147, v150, v151
	v_add_f32_dpp v132, v132, v132 row_ror:8 row_mask:0xf bank_mask:0x3
	v_add_f32_dpp v133, v133, v133 row_ror:8 row_mask:0xf bank_mask:0x3
	v_add_f32_dpp v134, v134, v134 row_ror:8 row_mask:0xf bank_mask:0x3
	v_add_f32_dpp v135, v135, v135 row_ror:8 row_mask:0xf bank_mask:0x3
	v_add_f32_dpp v136, v136, v136 row_ror:8 row_mask:0xf bank_mask:0x3
	v_add_f32_dpp v137, v137, v137 row_ror:8 row_mask:0xf bank_mask:0x3
	v_add_f32_dpp v138, v138, v138 row_ror:8 row_mask:0xf bank_mask:0x3
	v_add_f32_dpp v139, v139, v139 row_ror:8 row_mask:0xf bank_mask:0x3
	v_add_f32_dpp v132, v140, v140 row_ror:8 row_mask:0xf bank_mask:0xc
	v_add_f32_dpp v133, v141, v141 row_ror:8 row_mask:0xf bank_mask:0xc
	v_add_f32_dpp v134, v142, v142 row_ror:8 row_mask:0xf bank_mask:0xc
	v_add_f32_dpp v135, v143, v143 row_ror:8 row_mask:0xf bank_mask:0xc
	v_add_f32_dpp v136, v144, v144 row_ror:8 row_mask:0xf bank_mask:0xc
	v_add_f32_dpp v137, v145, v145 row_ror:8 row_mask:0xf bank_mask:0xc
	v_add_f32_dpp v138, v146, v146 row_ror:8 row_mask:0xf bank_mask:0xc
	v_add_f32_dpp v139, v147, v147 row_ror:8 row_mask:0xf bank_mask:0xc
	v_add_f32_dpp v132, v132, v132 row_ror:12 row_mask:0xf bank_mask:0x5
	v_add_f32_dpp v133, v133, v133 row_ror:12 row_mask:0xf bank_mask:0x5
	v_add_f32_dpp v134, v134, v134 row_ror:12 row_mask:0xf bank_mask:0x5
	v_add_f32_dpp v135, v135, v135 row_ror:12 row_mask:0xf bank_mask:0x5
	v_add_f32_dpp v132, v136, v136 row_ror:4 row_mask:0xf bank_mask:0xa
	v_add_f32_dpp v133, v137, v137 row_ror:4 row_mask:0xf bank_mask:0xa
	v_add_f32_dpp v134, v138, v138 row_ror:4 row_mask:0xf bank_mask:0xa
	v_add_f32_dpp v135, v139, v139 row_ror:4 row_mask:0xf bank_mask:0xa
	v_add_f32_dpp v140, v132, v132 quad_perm:[2,3,0,1] row_mask:0xf bank_mask:0xf
	v_add_f32_dpp v142, v134, v134 quad_perm:[2,3,0,1] row_mask:0xf bank_mask:0xf
	v_add_f32_dpp v141, v133, v133 quad_perm:[2,3,0,1] row_mask:0xf bank_mask:0xf
	v_add_f32_dpp v143, v135, v135 quad_perm:[2,3,0,1] row_mask:0xf bank_mask:0xf
	v_cndmask_b32_e64 v132, v140, v142, s[76:77]
	v_cndmask_b32_e64 v133, v141, v143, s[76:77]
	s_nop 0
	v_add_f32_dpp v196, v132, v132 quad_perm:[1,0,3,2] row_mask:0xf bank_mask:0xf
	v_add_f32_dpp v197, v133, v133 quad_perm:[1,0,3,2] row_mask:0xf bank_mask:0xf
	v_cndmask_b32_e64 v176, v196, v197, s[78:79]
	s_waitcnt vmcnt(34)
	v_pk_mul_f32 v[148:149], v[68:69], v[152:153]
	v_pk_fma_f32 v[148:149], v[70:71], v[154:155], v[148:149]
	global_load_dwordx4 v[68:71], v187, s[66:67] nt
	s_add_u32 s66, s66, 0x2000
	s_addc_u32 s67, s67, 0
	v_add_f32_e32 v132, v148, v149
	s_waitcnt vmcnt(34)
	v_pk_mul_f32 v[150:151], v[72:73], v[152:153]
	v_pk_fma_f32 v[150:151], v[74:75], v[154:155], v[150:151]
	global_load_dwordx4 v[72:75], v187, s[66:67] nt
	s_add_u32 s66, s66, 0x2000
	s_addc_u32 s67, s67, 0
	v_add_f32_e32 v133, v150, v151
	s_waitcnt vmcnt(34)
	v_pk_mul_f32 v[148:149], v[76:77], v[152:153]
	v_pk_fma_f32 v[148:149], v[78:79], v[154:155], v[148:149]
	global_load_dwordx4 v[76:79], v187, s[66:67] nt
	s_add_u32 s66, s66, 0x2000
	s_addc_u32 s67, s67, 0
	v_add_f32_e32 v134, v148, v149
	s_waitcnt vmcnt(34)
	v_pk_mul_f32 v[150:151], v[80:81], v[152:153]
	v_pk_fma_f32 v[150:151], v[82:83], v[154:155], v[150:151]
	global_load_dwordx4 v[80:83], v187, s[66:67] nt
	s_add_u32 s66, s66, 0x2000
	s_addc_u32 s67, s67, 0
	v_add_f32_e32 v135, v150, v151
	s_waitcnt vmcnt(34)
	v_pk_mul_f32 v[148:149], v[84:85], v[152:153]
	v_pk_fma_f32 v[148:149], v[86:87], v[154:155], v[148:149]
	global_load_dwordx4 v[84:87], v187, s[66:67] nt
	s_add_u32 s66, s66, 0x2000
	s_addc_u32 s67, s67, 0
	v_add_f32_e32 v136, v148, v149
	s_waitcnt vmcnt(34)
	v_pk_mul_f32 v[150:151], v[88:89], v[152:153]
	v_pk_fma_f32 v[150:151], v[90:91], v[154:155], v[150:151]
	global_load_dwordx4 v[88:91], v187, s[66:67] nt
	s_add_u32 s66, s66, 0x2000
	s_addc_u32 s67, s67, 0
	v_add_f32_e32 v137, v150, v151
	s_waitcnt vmcnt(34)
	v_pk_mul_f32 v[148:149], v[92:93], v[152:153]
	v_pk_fma_f32 v[148:149], v[94:95], v[154:155], v[148:149]
	global_load_dwordx4 v[92:95], v187, s[66:67] nt
	s_add_u32 s66, s66, 0x2000
	s_addc_u32 s67, s67, 0
	v_add_f32_e32 v138, v148, v149
	s_waitcnt vmcnt(34)
	v_pk_mul_f32 v[150:151], v[96:97], v[152:153]
	v_pk_fma_f32 v[150:151], v[98:99], v[154:155], v[150:151]
	global_load_dwordx4 v[96:99], v187, s[66:67] nt
	s_add_u32 s66, s66, 0x2000
	s_addc_u32 s67, s67, 0
	v_add_f32_e32 v139, v150, v151
	s_waitcnt vmcnt(34)
	v_pk_mul_f32 v[148:149], v[100:101], v[152:153]
	v_pk_fma_f32 v[148:149], v[102:103], v[154:155], v[148:149]
	global_load_dwordx4 v[100:103], v187, s[66:67] nt
	s_add_u32 s66, s66, 0x2000
	s_addc_u32 s67, s67, 0
	v_add_f32_e32 v140, v148, v149
	s_waitcnt vmcnt(34)
	v_pk_mul_f32 v[150:151], v[104:105], v[152:153]
	v_pk_fma_f32 v[150:151], v[106:107], v[154:155], v[150:151]
	global_load_dwordx4 v[104:107], v187, s[66:67] nt
	s_add_u32 s66, s66, 0x2000
	s_addc_u32 s67, s67, 0
	v_add_f32_e32 v141, v150, v151
	s_waitcnt vmcnt(34)
	v_pk_mul_f32 v[148:149], v[108:109], v[152:153]
	v_pk_fma_f32 v[148:149], v[110:111], v[154:155], v[148:149]
	global_load_dwordx4 v[108:111], v187, s[66:67] nt
	s_add_u32 s66, s66, 0x2000
	s_addc_u32 s67, s67, 0
	v_add_f32_e32 v142, v148, v149
	s_waitcnt vmcnt(34)
	v_pk_mul_f32 v[150:151], v[112:113], v[152:153]
	v_pk_fma_f32 v[150:151], v[114:115], v[154:155], v[150:151]
	global_load_dwordx4 v[112:115], v187, s[66:67] nt
	s_add_u32 s66, s66, 0x2000
	s_addc_u32 s67, s67, 0
	v_add_f32_e32 v143, v150, v151
	s_waitcnt vmcnt(34)
	v_pk_mul_f32 v[148:149], v[116:117], v[152:153]
	v_pk_fma_f32 v[148:149], v[118:119], v[154:155], v[148:149]
	global_load_dwordx4 v[116:119], v187, s[66:67] nt
	s_add_u32 s66, s66, 0x2000
	s_addc_u32 s67, s67, 0
	v_add_f32_e32 v144, v148, v149
	s_waitcnt vmcnt(34)
	v_pk_mul_f32 v[150:151], v[120:121], v[152:153]
	v_pk_fma_f32 v[150:151], v[122:123], v[154:155], v[150:151]
	global_load_dwordx4 v[120:123], v187, s[66:67] nt
	s_add_u32 s66, s66, 0x2000
	s_addc_u32 s67, s67, 0
	v_add_f32_e32 v145, v150, v151
	s_waitcnt vmcnt(34)
	v_pk_mul_f32 v[148:149], v[124:125], v[152:153]
	v_pk_fma_f32 v[148:149], v[126:127], v[154:155], v[148:149]
	global_load_dwordx4 v[124:127], v187, s[66:67] nt
	s_add_u32 s66, s66, 0x2000
	s_addc_u32 s67, s67, 0
	v_add_f32_e32 v146, v148, v149
	s_waitcnt vmcnt(34)
	v_pk_mul_f32 v[150:151], v[128:129], v[152:153]
	v_pk_fma_f32 v[150:151], v[130:131], v[154:155], v[150:151]
	global_load_dwordx4 v[128:131], v187, s[66:67] nt
	s_add_u32 s66, s66, 0x2000
	s_addc_u32 s67, s67, 0
	v_add_f32_e32 v147, v150, v151
	s_waitcnt vmcnt(32)
	v_readfirstlane_b32 s2, v191
	s_cmp_eq_u32 s35, 1
	s_cbranch_scc0 .Ldqa_nofetch
	v_mov_b32_e32 v200, s37
	s_cmp_eq_u32 s94, 0
	s_cbranch_scc0 .Ldqa_sh2
	v_mov_b32_e32 v201, s2
	ds_write_b32 v200, v201
	s_waitcnt lgkmcnt(0)
; __device__ __forceinline__ void sb_decode_stream(Frame& F, unsigned* qctr, int base, int limit) {
;     ...
;         const float z = __builtin_bit_cast(float, zi);
;         const float e = __builtin_amdgcn_exp2f(-(z * k1 + k2));
;         const float be = __builtin_amdgcn_rcpf(1.0f + e), m = 1.0f - be;
;         float s = m;
; #pragma unroll
;         for (int o = 1; o < 64; o <<= 1) { const float t = __shfl_down(s, o); if (lane + o < 64) s *= t; }
;         const float tot = __shfl(s, 0);
;         const float sx = __shfl_down(s, 1);
;         const float a = be * (lane < 63 ? sx : 1.0f);
;         int itn = (int)(__builtin_amdgcn_readfirstlane(vn) >> 6); const bool more = itn < limit; itn = more ? itn + base : it;
;         const int bn = itn >> 11, hn = itn & 7, p0n = ((itn >> 3) & 255) * 64;
;         const int pagen = PT[bn * NPAGES + (p0n >> 7)];
;         const size_t cbn = (((size_t)pagen * PAGE + (p0n & 127)) * NH + hn) * HD + lo;
;         const size_t stepn = more ? (size_t)(NH * HD) : 0;
;         f32x4 o4 = {0.f, 0.f, 0.f, 0.f};
; #pragma unroll
;         for (int i = 0; i < 16; ++i) { const float aj = __shfl(a, 2 * i + half); o4 += aj * A[i]; }
;         const f32x4 q4n = *(const f32x4*)(SSP(S_PROJ) + (size_t)bn * IN_COLS + hn * HD + 4 * l32);
; #pragma unroll
;         for (int i = 0; i < 16; ++i) A[i] = __builtin_nontemporal_load((const f32x4*)(CK + cbn + (size_t)(2 * i) * stepn));
.Ldqa_sh2:
	s_barrier
	ds_read_b32 v201, v200
	s_xor_b32 s37, s37, 4
	s_waitcnt lgkmcnt(0)
	v_readfirstlane_b32 s2, v201
	s_nop 0
	s_lshr_b32 s74, s2, 6
	s_mov_b32 s75, 1
	s_branch .Ldqa_havebase
.Ldqa_nofetch:
	s_nop 0
	s_add_u32 s74, s74, 8
	s_mov_b32 s75, 0
.Ldqa_havebase:
	s_nop 0
	s_mov_b32 s73, s74
	s_cmp_lt_u32 s73, 0x1800
	s_cselect_b32 s31, 1, 0
	s_add_u32 s73, s73, s94
	s_min_u32 s73, s73, 0x17ff
	s_cmp_eq_u32 s31, 1
	s_cselect_b32 s73, s73, s72
	s_lshr_b32 s6, s73, 11
	s_and_b32 s7, s73, 7
	s_bfe_u32 s8, s73, 0x80003
	s_lshl_b32 s9, s6, 7
	s_lshr_b32 s10, s8, 1
	s_or_b32 s9, s9, s10
	s_lshl_b32 s9, s9, 2
	s_lshl_b32 s10, s7, 2
	s_load_dword s29, s[54:55], s9
	s_load_dword s30, s[56:57], s10
	v_add_f32_dpp v132, v132, v132 row_ror:8 row_mask:0xf bank_mask:0x3
	v_add_f32_dpp v133, v133, v133 row_ror:8 row_mask:0xf bank_mask:0x3
	v_add_f32_dpp v134, v134, v134 row_ror:8 row_mask:0xf bank_mask:0x3
	v_add_f32_dpp v135, v135, v135 row_ror:8 row_mask:0xf bank_mask:0x3
	v_add_f32_dpp v136, v136, v136 row_ror:8 row_mask:0xf bank_mask:0x3
	v_add_f32_dpp v137, v137, v137 row_ror:8 row_mask:0xf bank_mask:0x3
	v_add_f32_dpp v138, v138, v138 row_ror:8 row_mask:0xf bank_mask:0x3
	v_add_f32_dpp v139, v139, v139 row_ror:8 row_mask:0xf bank_mask:0x3
	v_add_f32_dpp v132, v140, v140 row_ror:8 row_mask:0xf bank_mask:0xc
	v_add_f32_dpp v133, v141, v141 row_ror:8 row_mask:0xf bank_mask:0xc
	v_add_f32_dpp v134, v142, v142 row_ror:8 row_mask:0xf bank_mask:0xc
	v_add_f32_dpp v135, v143, v143 row_ror:8 row_mask:0xf bank_mask:0xc
	v_add_f32_dpp v136, v144, v144 row_ror:8 row_mask:0xf bank_mask:0xc
	v_add_f32_dpp v137, v145, v145 row_ror:8 row_mask:0xf bank_mask:0xc
	v_add_f32_dpp v138, v146, v146 row_ror:8 row_mask:0xf bank_mask:0xc
	v_add_f32_dpp v139, v147, v147 row_ror:8 row_mask:0xf bank_mask:0xc
	v_add_f32_dpp v132, v132, v132 row_ror:12 row_mask:0xf bank_mask:0x5
	v_add_f32_dpp v133, v133, v133 row_ror:12 row_mask:0xf bank_mask:0x5
	v_add_f32_dpp v134, v134, v134 row_ror:12 row_mask:0xf bank_mask:0x5
	v_add_f32_dpp v135, v135, v135 row_ror:12 row_mask:0xf bank_mask:0x5
	v_add_f32_dpp v132, v136, v136 row_ror:4 row_mask:0xf bank_mask:0xa
	v_add_f32_dpp v133, v137, v137 row_ror:4 row_mask:0xf bank_mask:0xa
	v_add_f32_dpp v134, v138, v138 row_ror:4 row_mask:0xf bank_mask:0xa
	v_add_f32_dpp v135, v139, v139 row_ror:4 row_mask:0xf bank_mask:0xa
	v_add_f32_dpp v140, v132, v132 quad_perm:[2,3,0,1] row_mask:0xf bank_mask:0xf
	v_add_f32_dpp v142, v134, v134 quad_perm:[2,3,0,1] row_mask:0xf bank_mask:0xf
	v_add_f32_dpp v141, v133, v133 quad_perm:[2,3,0,1] row_mask:0xf bank_mask:0xf
	v_add_f32_dpp v143, v135, v135 quad_perm:[2,3,0,1] row_mask:0xf bank_mask:0xf
	v_cndmask_b32_e64 v132, v140, v142, s[76:77]
	v_cndmask_b32_e64 v133, v141, v143, s[76:77]
	s_nop 0
	v_add_f32_dpp v196, v132, v132 quad_perm:[1,0,3,2] row_mask:0xf bank_mask:0xf
	v_add_f32_dpp v197, v133, v133 quad_perm:[1,0,3,2] row_mask:0xf bank_mask:0xf
	v_cndmask_b32_e64 v177, v196, v197, s[78:79]
	s_nop 1
	v_permlane16_swap_b32_e32 v176, v177
	v_add_f32_e32 v178, v176, v177
	v_mul_f32_e32 v178, 0x3e0293ee, v178
	v_add_f32_e32 v178, v178, v192
	v_exp_f32_e64 v198, -v178
	s_nop 0
	v_add_f32_e32 v198, 1.0, v198
	v_rcp_f32_e32 v179, v198
	s_nop 0
	v_sub_f32_e32 v180, 1.0, v179
	v_mov_b32_e32 v181, v180
	s_nop 1
	v_permlane32_swap_b32_e32 v180, v181
	v_mul_f32_e32 v183, v180, v181
	s_nop 1
	v_mul_f32_dpp v183, v183, v183 row_shl:1 row_mask:0xf bank_mask:0xf
	s_nop 1
	v_mul_f32_dpp v183, v183, v183 row_shl:2 row_mask:0xf bank_mask:0xf
	s_nop 1
	v_mul_f32_dpp v183, v183, v183 row_shl:4 row_mask:0xf bank_mask:0xf
	s_nop 1
	v_mul_f32_dpp v183, v183, v183 row_shl:8 row_mask:0xf bank_mask:0xf
	s_nop 0
	v_readlane_b32 s33, v183, 16
	v_mov_b32_e32 v184, 1.0
	s_nop 0
	v_mov_b32_e32 v185, s33
	s_nop 1
	v_mul_f32_dpp v183, v183, v185 quad_perm:[0,1,2,3] row_mask:0x5 bank_mask:0xf
	v_mov_b32_dpp v184, v185 quad_perm:[0,1,2,3] row_mask:0x5 bank_mask:0xf
	s_nop 1
	v_mov_b32_dpp v184, v183 row_shl:1 row_mask:0xf bank_mask:0xf
	v_mul_f32_e32 v186, v179, v184
	s_nop 1
	v_mul_f32_dpp v186, v186, v181 quad_perm:[0,1,2,3] row_mask:0x3 bank_mask:0xf
	s_cmp_eq_u32 s31, 0
	s_cbranch_scc1 .Ldqa_tail
	s_waitcnt lgkmcnt(0)
	s_mov_b32 s12, s29
	s_mov_b32 s13, 0
	s_lshl_b64 s[12:13], s[12:13], 19
	s_and_b32 s14, s8, 1
	s_lshl_b32 s14, s14, 18
	s_lshl_b32 s15, s7, 9
	s_or_b32 s14, s14, s15
	s_or_b32 s80, s12, s14
	s_mov_b32 s81, s13
	s_add_u32 s64, s50, s80
	s_addc_u32 s65, s51, s81
	s_mul_i32 s16, s6, 0x7040
	s_add_u32 s16, s16, s15
	s_add_u32 s16, s60, s16
	s_addc_u32 s17, s61, 0
	global_load_dwordx4 v[156:159], v193, s[16:17]
	v_mov_b32_e32 v160, 0
	v_mov_b32_e32 v161, 0
	v_mov_b32_e32 v162, 0
	v_mov_b32_e32 v163, 0
	v_mov_b32_e32 v164, 0
	v_mov_b32_e32 v165, 0
	v_mov_b32_e32 v166, 0
	v_mov_b32_e32 v167, 0
	ds_bpermute_b32 v168, v188, v186 offset:0
	ds_bpermute_b32 v170, v188, v186 offset:4
	ds_bpermute_b32 v172, v188, v186 offset:8
	ds_bpermute_b32 v174, v188, v186 offset:12
	s_waitcnt vmcnt(32) lgkmcnt(3)
	v_pk_fma_f32 v[160:161], v[4:5], v[168:169], v[160:161] op_sel_hi:[1,0,1]
	v_pk_fma_f32 v[162:163], v[6:7], v[168:169], v[162:163] op_sel_hi:[1,0,1]
	global_load_dwordx4 v[4:7], v187, s[64:65] nt
	s_add_u32 s64, s64, 0x2000
	s_addc_u32 s65, s65, 0
	ds_bpermute_b32 v168, v188, v186 offset:16
	s_waitcnt vmcnt(32) lgkmcnt(3)
	v_pk_fma_f32 v[164:165], v[8:9], v[170:171], v[164:165] op_sel_hi:[1,0,1]
	v_pk_fma_f32 v[166:167], v[10:11], v[170:171], v[166:167] op_sel_hi:[1,0,1]
	global_load_dwordx4 v[8:11], v187, s[64:65] nt
	s_add_u32 s64, s64, 0x2000
	s_addc_u32 s65, s65, 0
	ds_bpermute_b32 v170, v188, v186 offset:20
	s_waitcnt vmcnt(32) lgkmcnt(3)
; __device__ __forceinline__ void sb_decode_stream(Frame& F, unsigned* qctr, int base, int limit) {
;     ...
;         for (int i = 0; i < 16; ++i) { const float aj = __shfl(a, 2 * i + half); o4 += aj * A[i]; }
;         const f32x4 q4n = *(const f32x4*)(SSP(S_PROJ) + (size_t)bn * IN_COLS + hn * HD + 4 * l32);
; #pragma unroll
;         for (int i = 0; i < 16; ++i) A[i] = __builtin_nontemporal_load((const f32x4*)(CK + cbn + (size_t)(2 * i) * stepn));
	v_pk_fma_f32 v[160:161], v[12:13], v[172:173], v[160:161] op_sel_hi:[1,0,1]
	v_pk_fma_f32 v[162:163], v[14:15], v[172:173], v[162:163] op_sel_hi:[1,0,1]
	global_load_dwordx4 v[12:15], v187, s[64:65] nt
	s_add_u32 s64, s64, 0x2000
	s_addc_u32 s65, s65, 0
	ds_bpermute_b32 v172, v188, v186 offset:24
	s_waitcnt vmcnt(32) lgkmcnt(3)
	v_pk_fma_f32 v[164:165], v[16:17], v[174:175], v[164:165] op_sel_hi:[1,0,1]
	v_pk_fma_f32 v[166:167], v[18:19], v[174:175], v[166:167] op_sel_hi:[1,0,1]
	global_load_dwordx4 v[16:19], v187, s[64:65] nt
	s_add_u32 s64, s64, 0x2000
	s_addc_u32 s65, s65, 0
	ds_bpermute_b32 v174, v188, v186 offset:28
	s_waitcnt vmcnt(32) lgkmcnt(3)
	v_pk_fma_f32 v[160:161], v[20:21], v[168:169], v[160:161] op_sel_hi:[1,0,1]
	v_pk_fma_f32 v[162:163], v[22:23], v[168:169], v[162:163] op_sel_hi:[1,0,1]
	global_load_dwordx4 v[20:23], v187, s[64:65] nt
	s_add_u32 s64, s64, 0x2000
	s_addc_u32 s65, s65, 0
	ds_bpermute_b32 v168, v188, v186 offset:32
	s_waitcnt vmcnt(32) lgkmcnt(3)
	v_pk_fma_f32 v[164:165], v[24:25], v[170:171], v[164:165] op_sel_hi:[1,0,1]
	v_pk_fma_f32 v[166:167], v[26:27], v[170:171], v[166:167] op_sel_hi:[1,0,1]
	global_load_dwordx4 v[24:27], v187, s[64:65] nt
	s_add_u32 s64, s64, 0x2000
	s_addc_u32 s65, s65, 0
	ds_bpermute_b32 v170, v188, v186 offset:36
	s_waitcnt vmcnt(32) lgkmcnt(3)
	v_pk_fma_f32 v[160:161], v[28:29], v[172:173], v[160:161] op_sel_hi:[1,0,1]
	v_pk_fma_f32 v[162:163], v[30:31], v[172:173], v[162:163] op_sel_hi:[1,0,1]
	global_load_dwordx4 v[28:31], v187, s[64:65] nt
	s_add_u32 s64, s64, 0x2000
	s_addc_u32 s65, s65, 0
	ds_bpermute_b32 v172, v188, v186 offset:40
	s_waitcnt vmcnt(32) lgkmcnt(3)
	v_pk_fma_f32 v[164:165], v[32:33], v[174:175], v[164:165] op_sel_hi:[1,0,1]
	v_pk_fma_f32 v[166:167], v[34:35], v[174:175], v[166:167] op_sel_hi:[1,0,1]
	global_load_dwordx4 v[32:35], v187, s[64:65] nt
	s_add_u32 s64, s64, 0x2000
	s_addc_u32 s65, s65, 0
	ds_bpermute_b32 v174, v188, v186 offset:44
	s_waitcnt vmcnt(32) lgkmcnt(3)
	v_pk_fma_f32 v[160:161], v[36:37], v[168:169], v[160:161] op_sel_hi:[1,0,1]
	v_pk_fma_f32 v[162:163], v[38:39], v[168:169], v[162:163] op_sel_hi:[1,0,1]
	global_load_dwordx4 v[36:39], v187, s[64:65] nt
	s_add_u32 s64, s64, 0x2000
	s_addc_u32 s65, s65, 0
	ds_bpermute_b32 v168, v188, v186 offset:48
	s_waitcnt vmcnt(32) lgkmcnt(3)
	v_pk_fma_f32 v[164:165], v[40:41], v[170:171], v[164:165] op_sel_hi:[1,0,1]
	v_pk_fma_f32 v[166:167], v[42:43], v[170:171], v[166:167] op_sel_hi:[1,0,1]
	global_load_dwordx4 v[40:43], v187, s[64:65] nt
	s_add_u32 s64, s64, 0x2000
	s_addc_u32 s65, s65, 0
	ds_bpermute_b32 v170, v188, v186 offset:52
	s_waitcnt vmcnt(32) lgkmcnt(3)
	v_pk_fma_f32 v[160:161], v[44:45], v[172:173], v[160:161] op_sel_hi:[1,0,1]
	v_pk_fma_f32 v[162:163], v[46:47], v[172:173], v[162:163] op_sel_hi:[1,0,1]
	global_load_dwordx4 v[44:47], v187, s[64:65] nt
	s_add_u32 s64, s64, 0x2000
	s_addc_u32 s65, s65, 0
	ds_bpermute_b32 v172, v188, v186 offset:56
	s_waitcnt vmcnt(32) lgkmcnt(3)
	v_pk_fma_f32 v[164:165], v[48:49], v[174:175], v[164:165] op_sel_hi:[1,0,1]
	v_pk_fma_f32 v[166:167], v[50:51], v[174:175], v[166:167] op_sel_hi:[1,0,1]
	global_load_dwordx4 v[48:51], v187, s[64:65] nt
	s_add_u32 s64, s64, 0x2000
	s_addc_u32 s65, s65, 0
	ds_bpermute_b32 v174, v188, v186 offset:60
	s_waitcnt vmcnt(32) lgkmcnt(3)
	v_pk_fma_f32 v[160:161], v[52:53], v[168:169], v[160:161] op_sel_hi:[1,0,1]
	v_pk_fma_f32 v[162:163], v[54:55], v[168:169], v[162:163] op_sel_hi:[1,0,1]
	global_load_dwordx4 v[52:55], v187, s[64:65] nt
	s_add_u32 s64, s64, 0x2000
	s_addc_u32 s65, s65, 0
	ds_bpermute_b32 v168, v188, v186 offset:64
	s_waitcnt vmcnt(32) lgkmcnt(3)
	v_pk_fma_f32 v[164:165], v[56:57], v[170:171], v[164:165] op_sel_hi:[1,0,1]
	v_pk_fma_f32 v[166:167], v[58:59], v[170:171], v[166:167] op_sel_hi:[1,0,1]
	global_load_dwordx4 v[56:59], v187, s[64:65] nt
	s_add_u32 s64, s64, 0x2000
	s_addc_u32 s65, s65, 0
	ds_bpermute_b32 v170, v188, v186 offset:68
	s_waitcnt vmcnt(32) lgkmcnt(3)
	v_pk_fma_f32 v[160:161], v[60:61], v[172:173], v[160:161] op_sel_hi:[1,0,1]
	v_pk_fma_f32 v[162:163], v[62:63], v[172:173], v[162:163] op_sel_hi:[1,0,1]
	global_load_dwordx4 v[60:63], v187, s[64:65] nt
	s_add_u32 s64, s64, 0x2000
	s_addc_u32 s65, s65, 0
	ds_bpermute_b32 v172, v188, v186 offset:72
	s_waitcnt vmcnt(32) lgkmcnt(3)
	v_pk_fma_f32 v[164:165], v[64:65], v[174:175], v[164:165] op_sel_hi:[1,0,1]
	v_pk_fma_f32 v[166:167], v[66:67], v[174:175], v[166:167] op_sel_hi:[1,0,1]
	global_load_dwordx4 v[64:67], v187, s[64:65] nt
	s_add_u32 s64, s64, 0x2000
	s_addc_u32 s65, s65, 0
	ds_bpermute_b32 v174, v188, v186 offset:76
	s_waitcnt vmcnt(32) lgkmcnt(3)
	v_pk_fma_f32 v[160:161], v[68:69], v[168:169], v[160:161] op_sel_hi:[1,0,1]
	v_pk_fma_f32 v[162:163], v[70:71], v[168:169], v[162:163] op_sel_hi:[1,0,1]
	global_load_dwordx4 v[68:71], v187, s[64:65] nt
	s_add_u32 s64, s64, 0x2000
	s_addc_u32 s65, s65, 0
	ds_bpermute_b32 v168, v188, v186 offset:80
	s_waitcnt vmcnt(32) lgkmcnt(3)
	v_pk_fma_f32 v[164:165], v[72:73], v[170:171], v[164:165] op_sel_hi:[1,0,1]
	v_pk_fma_f32 v[166:167], v[74:75], v[170:171], v[166:167] op_sel_hi:[1,0,1]
	global_load_dwordx4 v[72:75], v187, s[64:65] nt
	s_add_u32 s64, s64, 0x2000
	s_addc_u32 s65, s65, 0
	ds_bpermute_b32 v170, v188, v186 offset:84
	s_waitcnt vmcnt(32) lgkmcnt(3)
; __device__ __forceinline__ void sb_decode_stream(Frame& F, unsigned* qctr, int base, int limit) {
;     ...
;         for (int i = 0; i < 16; ++i) { const float aj = __shfl(a, 32 + 2 * i + half); o4 += aj * B[i]; }
; #pragma unroll
;         for (int i = 0; i < 16; ++i) B[i] = __builtin_nontemporal_load((const f32x4*)(CK + cbn + (size_t)(32 + 2 * i) * stepn));
;         o4.x += __shfl_xor(o4.x, 32); o4.y += __shfl_xor(o4.y, 32); o4.z += __shfl_xor(o4.z, 32); o4.w += __shfl_xor(o4.w, 32);
;         float* P = SSP(S_PART) + ((size_t)bh * DSEG + blk) * DPART;
;         if (half == 0) *(f32x4*)(P + 4 * l32) = o4; if (lane == 0) P[128] = tot;
;         if (!more) break;
;         it = itn; cb = cbn; q4 = q4n;
;     }
	v_pk_fma_f32 v[160:161], v[76:77], v[172:173], v[160:161] op_sel_hi:[1,0,1]
	v_pk_fma_f32 v[162:163], v[78:79], v[172:173], v[162:163] op_sel_hi:[1,0,1]
	global_load_dwordx4 v[76:79], v187, s[64:65] nt
	s_add_u32 s64, s64, 0x2000
	s_addc_u32 s65, s65, 0
	ds_bpermute_b32 v172, v188, v186 offset:88
	s_waitcnt vmcnt(32) lgkmcnt(3)
	v_pk_fma_f32 v[164:165], v[80:81], v[174:175], v[164:165] op_sel_hi:[1,0,1]
	v_pk_fma_f32 v[166:167], v[82:83], v[174:175], v[166:167] op_sel_hi:[1,0,1]
	global_load_dwordx4 v[80:83], v187, s[64:65] nt
	s_add_u32 s64, s64, 0x2000
	s_addc_u32 s65, s65, 0
	ds_bpermute_b32 v174, v188, v186 offset:92
	s_waitcnt vmcnt(32) lgkmcnt(3)
	v_pk_fma_f32 v[160:161], v[84:85], v[168:169], v[160:161] op_sel_hi:[1,0,1]
	v_pk_fma_f32 v[162:163], v[86:87], v[168:169], v[162:163] op_sel_hi:[1,0,1]
	global_load_dwordx4 v[84:87], v187, s[64:65] nt
	s_add_u32 s64, s64, 0x2000
	s_addc_u32 s65, s65, 0
	ds_bpermute_b32 v168, v188, v186 offset:96
	s_waitcnt vmcnt(32) lgkmcnt(3)
	v_pk_fma_f32 v[164:165], v[88:89], v[170:171], v[164:165] op_sel_hi:[1,0,1]
	v_pk_fma_f32 v[166:167], v[90:91], v[170:171], v[166:167] op_sel_hi:[1,0,1]
	global_load_dwordx4 v[88:91], v187, s[64:65] nt
	s_add_u32 s64, s64, 0x2000
	s_addc_u32 s65, s65, 0
	ds_bpermute_b32 v170, v188, v186 offset:100
	s_waitcnt vmcnt(32) lgkmcnt(3)
	v_pk_fma_f32 v[160:161], v[92:93], v[172:173], v[160:161] op_sel_hi:[1,0,1]
	v_pk_fma_f32 v[162:163], v[94:95], v[172:173], v[162:163] op_sel_hi:[1,0,1]
	global_load_dwordx4 v[92:95], v187, s[64:65] nt
	s_add_u32 s64, s64, 0x2000
	s_addc_u32 s65, s65, 0
	ds_bpermute_b32 v172, v188, v186 offset:104
	s_waitcnt vmcnt(32) lgkmcnt(3)
	v_pk_fma_f32 v[164:165], v[96:97], v[174:175], v[164:165] op_sel_hi:[1,0,1]
	v_pk_fma_f32 v[166:167], v[98:99], v[174:175], v[166:167] op_sel_hi:[1,0,1]
	global_load_dwordx4 v[96:99], v187, s[64:65] nt
	s_add_u32 s64, s64, 0x2000
	s_addc_u32 s65, s65, 0
	ds_bpermute_b32 v174, v188, v186 offset:108
	s_waitcnt vmcnt(32) lgkmcnt(3)
	v_pk_fma_f32 v[160:161], v[100:101], v[168:169], v[160:161] op_sel_hi:[1,0,1]
	v_pk_fma_f32 v[162:163], v[102:103], v[168:169], v[162:163] op_sel_hi:[1,0,1]
	global_load_dwordx4 v[100:103], v187, s[64:65] nt
	s_add_u32 s64, s64, 0x2000
	s_addc_u32 s65, s65, 0
	ds_bpermute_b32 v168, v188, v186 offset:112
	s_waitcnt vmcnt(32) lgkmcnt(3)
	v_pk_fma_f32 v[164:165], v[104:105], v[170:171], v[164:165] op_sel_hi:[1,0,1]
	v_pk_fma_f32 v[166:167], v[106:107], v[170:171], v[166:167] op_sel_hi:[1,0,1]
	global_load_dwordx4 v[104:107], v187, s[64:65] nt
	s_add_u32 s64, s64, 0x2000
	s_addc_u32 s65, s65, 0
	ds_bpermute_b32 v170, v188, v186 offset:116
	s_waitcnt vmcnt(32) lgkmcnt(3)
	v_pk_fma_f32 v[160:161], v[108:109], v[172:173], v[160:161] op_sel_hi:[1,0,1]
	v_pk_fma_f32 v[162:163], v[110:111], v[172:173], v[162:163] op_sel_hi:[1,0,1]
	global_load_dwordx4 v[108:111], v187, s[64:65] nt
	s_add_u32 s64, s64, 0x2000
	s_addc_u32 s65, s65, 0
	ds_bpermute_b32 v172, v188, v186 offset:120
	s_waitcnt vmcnt(32) lgkmcnt(3)
	v_pk_fma_f32 v[164:165], v[112:113], v[174:175], v[164:165] op_sel_hi:[1,0,1]
	v_pk_fma_f32 v[166:167], v[114:115], v[174:175], v[166:167] op_sel_hi:[1,0,1]
	global_load_dwordx4 v[112:115], v187, s[64:65] nt
	s_add_u32 s64, s64, 0x2000
	s_addc_u32 s65, s65, 0
	ds_bpermute_b32 v174, v188, v186 offset:124
	s_waitcnt vmcnt(32) lgkmcnt(3)
	v_pk_fma_f32 v[160:161], v[116:117], v[168:169], v[160:161] op_sel_hi:[1,0,1]
	v_pk_fma_f32 v[162:163], v[118:119], v[168:169], v[162:163] op_sel_hi:[1,0,1]
	global_load_dwordx4 v[116:119], v187, s[64:65] nt
	s_add_u32 s64, s64, 0x2000
	s_addc_u32 s65, s65, 0
	s_waitcnt vmcnt(32) lgkmcnt(2)
	v_pk_fma_f32 v[164:165], v[120:121], v[170:171], v[164:165] op_sel_hi:[1,0,1]
	v_pk_fma_f32 v[166:167], v[122:123], v[170:171], v[166:167] op_sel_hi:[1,0,1]
	global_load_dwordx4 v[120:123], v187, s[64:65] nt
	s_add_u32 s64, s64, 0x2000
	s_addc_u32 s65, s65, 0
	s_waitcnt vmcnt(32) lgkmcnt(1)
	v_pk_fma_f32 v[160:161], v[124:125], v[172:173], v[160:161] op_sel_hi:[1,0,1]
	v_pk_fma_f32 v[162:163], v[126:127], v[172:173], v[162:163] op_sel_hi:[1,0,1]
	global_load_dwordx4 v[124:127], v187, s[64:65] nt
	s_add_u32 s64, s64, 0x2000
	s_addc_u32 s65, s65, 0
	s_waitcnt vmcnt(32) lgkmcnt(0)
	v_pk_fma_f32 v[164:165], v[128:129], v[174:175], v[164:165] op_sel_hi:[1,0,1]
	v_pk_fma_f32 v[166:167], v[130:131], v[174:175], v[166:167] op_sel_hi:[1,0,1]
	global_load_dwordx4 v[128:131], v187, s[64:65] nt
	s_add_u32 s64, s64, 0x2000
	s_addc_u32 s65, s65, 0
	s_nop 1
	v_pk_add_f32 v[160:161], v[160:161], v[164:165]
	v_pk_add_f32 v[162:163], v[162:163], v[166:167]
	s_nop 1
	v_mov_b32_e32 v164, v160
	v_mov_b32_e32 v165, v161
	v_mov_b32_e32 v166, v162
	v_mov_b32_e32 v167, v163
	v_permlane32_swap_b32_e32 v160, v164
	v_permlane32_swap_b32_e32 v161, v165
	v_permlane32_swap_b32_e32 v162, v166
	v_permlane32_swap_b32_e32 v163, v167
	v_pk_add_f32 v[160:161], v[160:161], v[164:165]
	v_pk_add_f32 v[162:163], v[162:163], v[166:167]
	s_nop 1
	s_mov_b32 exec_hi, 0
	global_store_dwordx4 v193, v[160:163], s[70:71]
	s_mov_b32 exec_lo, 1
	global_store_dword v189, v183, s[70:71] offset:512
	s_mov_b64 exec, -1
	s_mov_b32 s72, s73
	s_branch .Ldqa_loop

; __device__ __forceinline__ void sb_decode_stream(Frame& F, unsigned* qctr, int base, int limit) {
;     const float* CK = kin(2); const float* CV = kin(3); const int* PT = (const int*)kin(4);
;     int lane = F.lane; asm volatile("" : "+v"(lane));
;     const int half = lane >> 5, l32 = lane & 31;
;     const float k1 = SB_SCALE * 1.4426950408889634f;
;     const size_t lo = (size_t)half * (NH * HD) + 4 * l32;
;     int it;
;     { const unsigned v = __hip_atomic_fetch_add(qctr, 1u, __ATOMIC_RELAXED, __HIP_MEMORY_SCOPE_AGENT);
;       it = (int)(__builtin_amdgcn_readfirstlane(v) >> 6); if (it >= limit) return; it += base; }
; __global__ void __launch_bounds__(NWAVES * 64, 2) hymba_fwd(Args args) {
;     ...
;         if (!streamer) sb_decode_stream(F, F.ctl + CW_QUEUE, 0, DEC_Q2);
.LBB0_1294:
	s_load_dwordx2 s[50:51], s[0:1], 0x10
	s_load_dwordx2 s[52:53], s[0:1], 0x18
	s_load_dwordx2 s[54:55], s[0:1], 0x20
	s_load_dwordx2 s[56:57], s[0:1], 0x60
	s_add_u32 s58, s26, 0x1000
	s_addc_u32 s59, s27, 0
	s_add_u32 s60, s26, 0x2ff18000
	s_addc_u32 s61, s27, 0
	s_add_u32 s62, s26, 0x2ff70400
	s_addc_u32 s63, s27, 0
	s_mov_b32 s76, 0xcccccccc
	s_mov_b32 s77, 0xcccccccc
	s_mov_b32 s78, 0xaaaaaaaa
	s_mov_b32 s79, 0xaaaaaaaa
	v_and_b32_e32 v193, 31, v199
	v_lshrrev_b32_e32 v188, 5, v199
	v_lshlrev_b32_e32 v193, 4, v193
	v_lshl_add_u32 v187, v188, 12, v193
	v_lshlrev_b32_e32 v188, 7, v188
	v_mov_b32_e32 v189, 0
	v_mov_b32_e32 v190, 64
	v_mov_b32_e32 v190, 0x400
	s_mov_b32 s37, 0x251e0
	s_cmp_eq_u32 s94, 0
	s_cbranch_scc0 .Ldqb_pro
	s_mov_b64 exec, 1
	global_atomic_add v191, v189, v190, s[58:59] sc0
	s_mov_b64 exec, -1

; __device__ __forceinline__ void sb_decode_stream(Frame& F, unsigned* qctr, int base, int limit) {
;     const float* CK = kin(2); const float* CV = kin(3); const int* PT = (const int*)kin(4);
;     int lane = F.lane; asm volatile("" : "+v"(lane));
;     const int half = lane >> 5, l32 = lane & 31;
;     const float k1 = SB_SCALE * 1.4426950408889634f;
;     const size_t lo = (size_t)half * (NH * HD) + 4 * l32;
;     int it;
;     { const unsigned v = __hip_atomic_fetch_add(qctr, 1u, __ATOMIC_RELAXED, __HIP_MEMORY_SCOPE_AGENT);
;       it = (int)(__builtin_amdgcn_readfirstlane(v) >> 6); if (it >= limit) return; it += base; }
; __device__ __forceinline__ void p2_mixers(Frame& F, unsigned* qctr) {
;     ...
;     const bool streamer = (F.bid >= NB * NH) && (((F.bid >> 3) - 2) % 5 < 2);
;     if (streamer) sb_decode_stream(F, qctr + 64, DEC_Q2, DEC_ITEMS - DEC_Q2);
.LBB0_1408:
	s_lshr_b32 s2, s96, 3
	s_mov_b32 s3, 0x8c6318c
	s_lshr_b32 s3, s3, s2
	s_and_b32 s3, s3, 1
	s_cmp_eq_u32 s3, 0
	s_cselect_b64 s[6:7], -1, 0
	s_add_u32 s38, s26, 0x1100
	s_addc_u32 s39, s27, 0
	s_add_u32 s3, s26, 0x2ff18000
	s_addc_u32 s4, s27, 0
	s_add_u32 s5, s26, 0x2ff70400
	s_addc_u32 s23, s27, 0
	s_or_b64 s[6:7], s[10:11], s[6:7]
	s_andn2_b64 vcc, exec, s[6:7]
	s_cbranch_vccz .LBB0_1420
	s_load_dwordx2 s[50:51], s[0:1], 0x10
	s_load_dwordx2 s[52:53], s[0:1], 0x18
	s_load_dwordx2 s[54:55], s[0:1], 0x20
	s_load_dwordx2 s[56:57], s[0:1], 0x60
	s_add_u32 s58, s26, 0x1100
	s_addc_u32 s59, s27, 0
	s_add_u32 s60, s26, 0x2ff18000
	s_addc_u32 s61, s27, 0
	s_add_u32 s62, s26, 0x2ff70400
	s_addc_u32 s63, s27, 0
	s_mov_b32 s76, 0xcccccccc
	s_mov_b32 s77, 0xcccccccc
	s_mov_b32 s78, 0xaaaaaaaa
	s_mov_b32 s79, 0xaaaaaaaa
	v_and_b32_e32 v193, 31, v199
	v_lshrrev_b32_e32 v188, 5, v199
	v_lshlrev_b32_e32 v193, 4, v193
	v_lshl_add_u32 v187, v188, 12, v193
	v_lshlrev_b32_e32 v188, 7, v188
	v_mov_b32_e32 v189, 0
	v_mov_b32_e32 v190, 64
	v_mov_b32_e32 v190, 0x400
	s_mov_b32 s37, 0x251e0
	s_cmp_eq_u32 s94, 0
	s_cbranch_scc0 .Ldqc_pro
	s_mov_b64 exec, 1
	global_atomic_add v191, v189, v190, s[58:59] sc0
	s_mov_b64 exec, -1

; __device__ __forceinline__ void sb_decode_stream(Frame& F, unsigned* qctr, int base, int limit) {
;     ...
;     { const unsigned v = __hip_atomic_fetch_add(qctr, 1u, __ATOMIC_RELAXED, __HIP_MEMORY_SCOPE_AGENT);
;       it = (int)(__builtin_amdgcn_readfirstlane(v) >> 6); if (it >= limit) return; it += base; }
;     f32x4 A[16], B[16], q4;
;     size_t cb;
;     { const int b = it >> 11, h = it & 7, p0 = ((it >> 3) & 255) * 64;
;       const int page = PT[b * NPAGES + (p0 >> 7)];
;       cb = (((size_t)page * PAGE + (p0 & 127)) * NH + h) * HD + lo;
;       q4 = *(const f32x4*)(SSP(S_PROJ) + (size_t)b * IN_COLS + h * HD + 4 * l32);
; #pragma unroll
;       for (int i = 0; i < 16; ++i) A[i] = __builtin_nontemporal_load((const f32x4*)(CK + cb + (size_t)(2 * i) * (NH * HD)));
; #pragma unroll
;       for (int i = 0; i < 16; ++i) B[i] = __builtin_nontemporal_load((const f32x4*)(CK + cb + (size_t)(32 + 2 * i) * (NH * HD))); }
.Ldqc_sh1:
	s_barrier
	ds_read_b32 v201, v200
	s_xor_b32 s37, s37, 4
	s_waitcnt lgkmcnt(0)
	v_readfirstlane_b32 s2, v201
	s_nop 0
	s_lshr_b32 s72, s2, 6
	s_cmp_ge_u32 s72, 0x2800
	s_cbranch_scc1 .Ldqc_exit
	s_mov_b32 s74, s72
	s_add_u32 s72, s72, s94
	s_min_u32 s72, s72, 0x27ff
	s_mov_b32 s75, 1
	s_add_u32 s72, s72, 0x1800
	s_waitcnt lgkmcnt(0)
	s_lshr_b32 s6, s72, 11
	s_and_b32 s7, s72, 7
	s_bfe_u32 s8, s72, 0x80003
	s_lshl_b32 s9, s6, 7
	s_lshr_b32 s10, s8, 1
	s_or_b32 s9, s9, s10
	s_lshl_b32 s9, s9, 2
	s_lshl_b32 s10, s7, 2
	s_load_dword s29, s[54:55], s9
	s_load_dword s30, s[56:57], s10
	s_waitcnt lgkmcnt(0)
	s_mov_b32 s12, s29
	s_mov_b32 s13, 0
	s_lshl_b64 s[12:13], s[12:13], 19
	s_and_b32 s14, s8, 1
	s_lshl_b32 s14, s14, 18
	s_lshl_b32 s15, s7, 9
	s_or_b32 s14, s14, s15
	s_or_b32 s80, s12, s14
	s_mov_b32 s81, s13
	s_add_u32 s64, s50, s80
	s_addc_u32 s65, s51, s81
	s_mul_i32 s16, s6, 0x7040
	s_add_u32 s16, s16, s15
	s_add_u32 s16, s60, s16
	s_addc_u32 s17, s61, 0
	global_load_dwordx4 v[156:159], v193, s[16:17]
	global_load_dwordx4 v[4:7], v187, s[64:65] nt
	s_add_u32 s64, s64, 0x2000
	s_addc_u32 s65, s65, 0
	global_load_dwordx4 v[8:11], v187, s[64:65] nt
	s_add_u32 s64, s64, 0x2000
	s_addc_u32 s65, s65, 0
	global_load_dwordx4 v[12:15], v187, s[64:65] nt
	s_add_u32 s64, s64, 0x2000
	s_addc_u32 s65, s65, 0
	global_load_dwordx4 v[16:19], v187, s[64:65] nt
	s_add_u32 s64, s64, 0x2000
	s_addc_u32 s65, s65, 0
	global_load_dwordx4 v[20:23], v187, s[64:65] nt
	s_add_u32 s64, s64, 0x2000
	s_addc_u32 s65, s65, 0
	global_load_dwordx4 v[24:27], v187, s[64:65] nt
	s_add_u32 s64, s64, 0x2000
	s_addc_u32 s65, s65, 0
	global_load_dwordx4 v[28:31], v187, s[64:65] nt
	s_add_u32 s64, s64, 0x2000
	s_addc_u32 s65, s65, 0
	global_load_dwordx4 v[32:35], v187, s[64:65] nt
	s_add_u32 s64, s64, 0x2000
	s_addc_u32 s65, s65, 0
	global_load_dwordx4 v[36:39], v187, s[64:65] nt
	s_add_u32 s64, s64, 0x2000
	s_addc_u32 s65, s65, 0
	global_load_dwordx4 v[40:43], v187, s[64:65] nt
	s_add_u32 s64, s64, 0x2000
	s_addc_u32 s65, s65, 0
	global_load_dwordx4 v[44:47], v187, s[64:65] nt
	s_add_u32 s64, s64, 0x2000
	s_addc_u32 s65, s65, 0
	global_load_dwordx4 v[48:51], v187, s[64:65] nt
	s_add_u32 s64, s64, 0x2000
	s_addc_u32 s65, s65, 0
	global_load_dwordx4 v[52:55], v187, s[64:65] nt
	s_add_u32 s64, s64, 0x2000
	s_addc_u32 s65, s65, 0
	global_load_dwordx4 v[56:59], v187, s[64:65] nt
	s_add_u32 s64, s64, 0x2000
	s_addc_u32 s65, s65, 0
	global_load_dwordx4 v[60:63], v187, s[64:65] nt
	s_add_u32 s64, s64, 0x2000
	s_addc_u32 s65, s65, 0
	global_load_dwordx4 v[64:67], v187, s[64:65] nt
	s_add_u32 s64, s64, 0x2000
	s_addc_u32 s65, s65, 0
	global_load_dwordx4 v[68:71], v187, s[64:65] nt
	s_add_u32 s64, s64, 0x2000
	s_addc_u32 s65, s65, 0
	global_load_dwordx4 v[72:75], v187, s[64:65] nt
	s_add_u32 s64, s64, 0x2000
	s_addc_u32 s65, s65, 0
	global_load_dwordx4 v[76:79], v187, s[64:65] nt
	s_add_u32 s64, s64, 0x2000
	s_addc_u32 s65, s65, 0
	global_load_dwordx4 v[80:83], v187, s[64:65] nt
	s_add_u32 s64, s64, 0x2000
	s_addc_u32 s65, s65, 0
	global_load_dwordx4 v[84:87], v187, s[64:65] nt
	s_add_u32 s64, s64, 0x2000
	s_addc_u32 s65, s65, 0
	global_load_dwordx4 v[88:91], v187, s[64:65] nt
	s_add_u32 s64, s64, 0x2000
	s_addc_u32 s65, s65, 0
	global_load_dwordx4 v[92:95], v187, s[64:65] nt
	s_add_u32 s64, s64, 0x2000
	s_addc_u32 s65, s65, 0
	global_load_dwordx4 v[96:99], v187, s[64:65] nt
	s_add_u32 s64, s64, 0x2000
	s_addc_u32 s65, s65, 0
	global_load_dwordx4 v[100:103], v187, s[64:65] nt
	s_add_u32 s64, s64, 0x2000
	s_addc_u32 s65, s65, 0
	global_load_dwordx4 v[104:107], v187, s[64:65] nt
	s_add_u32 s64, s64, 0x2000
	s_addc_u32 s65, s65, 0
	global_load_dwordx4 v[108:111], v187, s[64:65] nt
	s_add_u32 s64, s64, 0x2000
	s_addc_u32 s65, s65, 0
	global_load_dwordx4 v[112:115], v187, s[64:65] nt
	s_add_u32 s64, s64, 0x2000
	s_addc_u32 s65, s65, 0
	global_load_dwordx4 v[116:119], v187, s[64:65] nt
	s_add_u32 s64, s64, 0x2000
	s_addc_u32 s65, s65, 0
	global_load_dwordx4 v[120:123], v187, s[64:65] nt
	s_add_u32 s64, s64, 0x2000
	s_addc_u32 s65, s65, 0
	global_load_dwordx4 v[124:127], v187, s[64:65] nt
	s_add_u32 s64, s64, 0x2000
	s_addc_u32 s65, s65, 0
	global_load_dwordx4 v[128:131], v187, s[64:65] nt
	s_add_u32 s64, s64, 0x2000
	s_addc_u32 s65, s65, 0
	global_load_dword v194, v189, s[58:59]
	global_load_dword v195, v189, s[58:59]

; __device__ __forceinline__ void sb_decode_stream(Frame& F, unsigned* qctr, int base, int limit) {
;     ...
;         const float z = __builtin_bit_cast(float, zi);
;         const float e = __builtin_amdgcn_exp2f(-(z * k1 + k2));
;         const float be = __builtin_amdgcn_rcpf(1.0f + e), m = 1.0f - be;
;         float s = m;
; #pragma unroll
;         for (int o = 1; o < 64; o <<= 1) { const float t = __shfl_down(s, o); if (lane + o < 64) s *= t; }
;         const float tot = __shfl(s, 0);
;         const float sx = __shfl_down(s, 1);
;         const float a = be * (lane < 63 ? sx : 1.0f);
;         int itn = (int)(__builtin_amdgcn_readfirstlane(vn) >> 6); const bool more = itn < limit; itn = more ? itn + base : it;
;         const int bn = itn >> 11, hn = itn & 7, p0n = ((itn >> 3) & 255) * 64;
;         const int pagen = PT[bn * NPAGES + (p0n >> 7)];
;         const size_t cbn = (((size_t)pagen * PAGE + (p0n & 127)) * NH + hn) * HD + lo;
;         const size_t stepn = more ? (size_t)(NH * HD) : 0;
;         f32x4 o4 = {0.f, 0.f, 0.f, 0.f};
; #pragma unroll
;         for (int i = 0; i < 16; ++i) { const float aj = __shfl(a, 2 * i + half); o4 += aj * A[i]; }
.Ldqc_havebase:
	s_nop 0
	s_mov_b32 s73, s74
	s_cmp_lt_u32 s73, 0x2800
	s_cselect_b32 s31, 1, 0
	s_add_u32 s73, s73, s94
	s_min_u32 s73, s73, 0x27ff
	s_add_u32 s73, s73, 0x1800
	s_cmp_eq_u32 s31, 1
	s_cselect_b32 s73, s73, s72
	s_lshr_b32 s6, s73, 11
	s_and_b32 s7, s73, 7
	s_bfe_u32 s8, s73, 0x80003
	s_lshl_b32 s9, s6, 7
	s_lshr_b32 s10, s8, 1
	s_or_b32 s9, s9, s10
	s_lshl_b32 s9, s9, 2
	s_lshl_b32 s10, s7, 2
	s_load_dword s29, s[54:55], s9
	s_load_dword s30, s[56:57], s10
	v_add_f32_dpp v132, v132, v132 row_ror:8 row_mask:0xf bank_mask:0x3
	v_add_f32_dpp v133, v133, v133 row_ror:8 row_mask:0xf bank_mask:0x3
	v_add_f32_dpp v134, v134, v134 row_ror:8 row_mask:0xf bank_mask:0x3
	v_add_f32_dpp v135, v135, v135 row_ror:8 row_mask:0xf bank_mask:0x3
	v_add_f32_dpp v136, v136, v136 row_ror:8 row_mask:0xf bank_mask:0x3
	v_add_f32_dpp v137, v137, v137 row_ror:8 row_mask:0xf bank_mask:0x3
	v_add_f32_dpp v138, v138, v138 row_ror:8 row_mask:0xf bank_mask:0x3
	v_add_f32_dpp v139, v139, v139 row_ror:8 row_mask:0xf bank_mask:0x3
	v_add_f32_dpp v132, v140, v140 row_ror:8 row_mask:0xf bank_mask:0xc
	v_add_f32_dpp v133, v141, v141 row_ror:8 row_mask:0xf bank_mask:0xc
	v_add_f32_dpp v134, v142, v142 row_ror:8 row_mask:0xf bank_mask:0xc
	v_add_f32_dpp v135, v143, v143 row_ror:8 row_mask:0xf bank_mask:0xc
	v_add_f32_dpp v136, v144, v144 row_ror:8 row_mask:0xf bank_mask:0xc
	v_add_f32_dpp v137, v145, v145 row_ror:8 row_mask:0xf bank_mask:0xc
	v_add_f32_dpp v138, v146, v146 row_ror:8 row_mask:0xf bank_mask:0xc
	v_add_f32_dpp v139, v147, v147 row_ror:8 row_mask:0xf bank_mask:0xc
	v_add_f32_dpp v132, v132, v132 row_ror:12 row_mask:0xf bank_mask:0x5
	v_add_f32_dpp v133, v133, v133 row_ror:12 row_mask:0xf bank_mask:0x5
	v_add_f32_dpp v134, v134, v134 row_ror:12 row_mask:0xf bank_mask:0x5
	v_add_f32_dpp v135, v135, v135 row_ror:12 row_mask:0xf bank_mask:0x5
	v_add_f32_dpp v132, v136, v136 row_ror:4 row_mask:0xf bank_mask:0xa
	v_add_f32_dpp v133, v137, v137 row_ror:4 row_mask:0xf bank_mask:0xa
	v_add_f32_dpp v134, v138, v138 row_ror:4 row_mask:0xf bank_mask:0xa
	v_add_f32_dpp v135, v139, v139 row_ror:4 row_mask:0xf bank_mask:0xa
	v_add_f32_dpp v140, v132, v132 quad_perm:[2,3,0,1] row_mask:0xf bank_mask:0xf
	v_add_f32_dpp v142, v134, v134 quad_perm:[2,3,0,1] row_mask:0xf bank_mask:0xf
	v_add_f32_dpp v141, v133, v133 quad_perm:[2,3,0,1] row_mask:0xf bank_mask:0xf
	v_add_f32_dpp v143, v135, v135 quad_perm:[2,3,0,1] row_mask:0xf bank_mask:0xf
	v_cndmask_b32_e64 v132, v140, v142, s[76:77]
	v_cndmask_b32_e64 v133, v141, v143, s[76:77]
	s_nop 0
	v_add_f32_dpp v196, v132, v132 quad_perm:[1,0,3,2] row_mask:0xf bank_mask:0xf
	v_add_f32_dpp v197, v133, v133 quad_perm:[1,0,3,2] row_mask:0xf bank_mask:0xf
	v_cndmask_b32_e64 v177, v196, v197, s[78:79]
	s_nop 1
	v_permlane16_swap_b32_e32 v176, v177
	v_add_f32_e32 v178, v176, v177
	v_mul_f32_e32 v178, 0x3e0293ee, v178
	v_add_f32_e32 v178, v178, v192
	v_exp_f32_e64 v198, -v178
	s_nop 0
	v_add_f32_e32 v198, 1.0, v198
	v_rcp_f32_e32 v179, v198
	s_nop 0
	v_sub_f32_e32 v180, 1.0, v179
	v_mov_b32_e32 v181, v180
	s_nop 1
	v_permlane32_swap_b32_e32 v180, v181
	v_mul_f32_e32 v183, v180, v181
	s_nop 1
	v_mul_f32_dpp v183, v183, v183 row_shl:1 row_mask:0xf bank_mask:0xf
	s_nop 1
	v_mul_f32_dpp v183, v183, v183 row_shl:2 row_mask:0xf bank_mask:0xf
	s_nop 1
	v_mul_f32_dpp v183, v183, v183 row_shl:4 row_mask:0xf bank_mask:0xf
	s_nop 1
	v_mul_f32_dpp v183, v183, v183 row_shl:8 row_mask:0xf bank_mask:0xf
	s_nop 0
	v_readlane_b32 s33, v183, 16
	v_mov_b32_e32 v184, 1.0
	s_nop 0
	v_mov_b32_e32 v185, s33
	s_nop 1
	v_mul_f32_dpp v183, v183, v185 quad_perm:[0,1,2,3] row_mask:0x5 bank_mask:0xf
	v_mov_b32_dpp v184, v185 quad_perm:[0,1,2,3] row_mask:0x5 bank_mask:0xf
	s_nop 1
	v_mov_b32_dpp v184, v183 row_shl:1 row_mask:0xf bank_mask:0xf
	v_mul_f32_e32 v186, v179, v184
	s_nop 1
	v_mul_f32_dpp v186, v186, v181 quad_perm:[0,1,2,3] row_mask:0x3 bank_mask:0xf
	s_cmp_eq_u32 s31, 0
	s_cbranch_scc1 .Ldqc_tail
	s_waitcnt lgkmcnt(0)
	s_mov_b32 s12, s29
	s_mov_b32 s13, 0
	s_lshl_b64 s[12:13], s[12:13], 19
	s_and_b32 s14, s8, 1
	s_lshl_b32 s14, s14, 18
	s_lshl_b32 s15, s7, 9
	s_or_b32 s14, s14, s15
	s_or_b32 s80, s12, s14
	s_mov_b32 s81, s13
	s_add_u32 s64, s50, s80
	s_addc_u32 s65, s51, s81
	s_mul_i32 s16, s6, 0x7040
	s_add_u32 s16, s16, s15
	s_add_u32 s16, s60, s16
	s_addc_u32 s17, s61, 0
	global_load_dwordx4 v[156:159], v193, s[16:17]
	v_mov_b32_e32 v160, 0
	v_mov_b32_e32 v161, 0
	v_mov_b32_e32 v162, 0
	v_mov_b32_e32 v163, 0
	v_mov_b32_e32 v164, 0
	v_mov_b32_e32 v165, 0
	v_mov_b32_e32 v166, 0
	v_mov_b32_e32 v167, 0
	ds_bpermute_b32 v168, v188, v186 offset:0
	ds_bpermute_b32 v170, v188, v186 offset:4
	ds_bpermute_b32 v172, v188, v186 offset:8
	ds_bpermute_b32 v174, v188, v186 offset:12
	s_waitcnt vmcnt(32) lgkmcnt(3)
	v_pk_fma_f32 v[160:161], v[4:5], v[168:169], v[160:161] op_sel_hi:[1,0,1]
	v_pk_fma_f32 v[162:163], v[6:7], v[168:169], v[162:163] op_sel_hi:[1,0,1]
	global_load_dwordx4 v[4:7], v187, s[64:65] nt
	s_add_u32 s64, s64, 0x2000
	s_addc_u32 s65, s65, 0
	ds_bpermute_b32 v168, v188, v186 offset:16
	s_waitcnt vmcnt(32) lgkmcnt(3)
	v_pk_fma_f32 v[164:165], v[8:9], v[170:171], v[164:165] op_sel_hi:[1,0,1]
	v_pk_fma_f32 v[166:167], v[10:11], v[170:171], v[166:167] op_sel_hi:[1,0,1]
	global_load_dwordx4 v[8:11], v187, s[64:65] nt
	s_add_u32 s64, s64, 0x2000
	s_addc_u32 s65, s65, 0
	ds_bpermute_b32 v170, v188, v186 offset:20
	s_waitcnt vmcnt(32) lgkmcnt(3)
	v_pk_fma_f32 v[160:161], v[12:13], v[172:173], v[160:161] op_sel_hi:[1,0,1]
	v_pk_fma_f32 v[162:163], v[14:15], v[172:173], v[162:163] op_sel_hi:[1,0,1]
	global_load_dwordx4 v[12:15], v187, s[64:65] nt
	s_add_u32 s64, s64, 0x2000
	s_addc_u32 s65, s65, 0
	ds_bpermute_b32 v172, v188, v186 offset:24
	s_waitcnt vmcnt(32) lgkmcnt(3)
; __device__ __forceinline__ void sb_decode_stream(Frame& F, unsigned* qctr, int base, int limit) {
;     ...
;         f32x4 o4 = {0.f, 0.f, 0.f, 0.f};
; #pragma unroll
;         for (int i = 0; i < 16; ++i) { const float aj = __shfl(a, 2 * i + half); o4 += aj * A[i]; }
;         const f32x4 q4n = *(const f32x4*)(SSP(S_PROJ) + (size_t)bn * IN_COLS + hn * HD + 4 * l32);
; #pragma unroll
;         for (int i = 0; i < 16; ++i) A[i] = __builtin_nontemporal_load((const f32x4*)(CK + cbn + (size_t)(2 * i) * stepn));
; #pragma unroll
;         for (int i = 0; i < 16; ++i) { const float aj = __shfl(a, 32 + 2 * i + half); o4 += aj * B[i]; }
; #pragma unroll
;         for (int i = 0; i < 16; ++i) B[i] = __builtin_nontemporal_load((const f32x4*)(CK + cbn + (size_t)(32 + 2 * i) * stepn));
	v_pk_fma_f32 v[164:165], v[16:17], v[174:175], v[164:165] op_sel_hi:[1,0,1]
	v_pk_fma_f32 v[166:167], v[18:19], v[174:175], v[166:167] op_sel_hi:[1,0,1]
	global_load_dwordx4 v[16:19], v187, s[64:65] nt
	s_add_u32 s64, s64, 0x2000
	s_addc_u32 s65, s65, 0
	ds_bpermute_b32 v174, v188, v186 offset:28
	s_waitcnt vmcnt(32) lgkmcnt(3)
	v_pk_fma_f32 v[160:161], v[20:21], v[168:169], v[160:161] op_sel_hi:[1,0,1]
	v_pk_fma_f32 v[162:163], v[22:23], v[168:169], v[162:163] op_sel_hi:[1,0,1]
	global_load_dwordx4 v[20:23], v187, s[64:65] nt
	s_add_u32 s64, s64, 0x2000
	s_addc_u32 s65, s65, 0
	ds_bpermute_b32 v168, v188, v186 offset:32
	s_waitcnt vmcnt(32) lgkmcnt(3)
	v_pk_fma_f32 v[164:165], v[24:25], v[170:171], v[164:165] op_sel_hi:[1,0,1]
	v_pk_fma_f32 v[166:167], v[26:27], v[170:171], v[166:167] op_sel_hi:[1,0,1]
	global_load_dwordx4 v[24:27], v187, s[64:65] nt
	s_add_u32 s64, s64, 0x2000
	s_addc_u32 s65, s65, 0
	ds_bpermute_b32 v170, v188, v186 offset:36
	s_waitcnt vmcnt(32) lgkmcnt(3)
	v_pk_fma_f32 v[160:161], v[28:29], v[172:173], v[160:161] op_sel_hi:[1,0,1]
	v_pk_fma_f32 v[162:163], v[30:31], v[172:173], v[162:163] op_sel_hi:[1,0,1]
	global_load_dwordx4 v[28:31], v187, s[64:65] nt
	s_add_u32 s64, s64, 0x2000
	s_addc_u32 s65, s65, 0
	ds_bpermute_b32 v172, v188, v186 offset:40
	s_waitcnt vmcnt(32) lgkmcnt(3)
	v_pk_fma_f32 v[164:165], v[32:33], v[174:175], v[164:165] op_sel_hi:[1,0,1]
	v_pk_fma_f32 v[166:167], v[34:35], v[174:175], v[166:167] op_sel_hi:[1,0,1]
	global_load_dwordx4 v[32:35], v187, s[64:65] nt
	s_add_u32 s64, s64, 0x2000
	s_addc_u32 s65, s65, 0
	ds_bpermute_b32 v174, v188, v186 offset:44
	s_waitcnt vmcnt(32) lgkmcnt(3)
	v_pk_fma_f32 v[160:161], v[36:37], v[168:169], v[160:161] op_sel_hi:[1,0,1]
	v_pk_fma_f32 v[162:163], v[38:39], v[168:169], v[162:163] op_sel_hi:[1,0,1]
	global_load_dwordx4 v[36:39], v187, s[64:65] nt
	s_add_u32 s64, s64, 0x2000
	s_addc_u32 s65, s65, 0
	ds_bpermute_b32 v168, v188, v186 offset:48
	s_waitcnt vmcnt(32) lgkmcnt(3)
	v_pk_fma_f32 v[164:165], v[40:41], v[170:171], v[164:165] op_sel_hi:[1,0,1]
	v_pk_fma_f32 v[166:167], v[42:43], v[170:171], v[166:167] op_sel_hi:[1,0,1]
	global_load_dwordx4 v[40:43], v187, s[64:65] nt
	s_add_u32 s64, s64, 0x2000
	s_addc_u32 s65, s65, 0
	ds_bpermute_b32 v170, v188, v186 offset:52
	s_waitcnt vmcnt(32) lgkmcnt(3)
	v_pk_fma_f32 v[160:161], v[44:45], v[172:173], v[160:161] op_sel_hi:[1,0,1]
	v_pk_fma_f32 v[162:163], v[46:47], v[172:173], v[162:163] op_sel_hi:[1,0,1]
	global_load_dwordx4 v[44:47], v187, s[64:65] nt
	s_add_u32 s64, s64, 0x2000
	s_addc_u32 s65, s65, 0
	ds_bpermute_b32 v172, v188, v186 offset:56
	s_waitcnt vmcnt(32) lgkmcnt(3)
	v_pk_fma_f32 v[164:165], v[48:49], v[174:175], v[164:165] op_sel_hi:[1,0,1]
	v_pk_fma_f32 v[166:167], v[50:51], v[174:175], v[166:167] op_sel_hi:[1,0,1]
	global_load_dwordx4 v[48:51], v187, s[64:65] nt
	s_add_u32 s64, s64, 0x2000
	s_addc_u32 s65, s65, 0
	ds_bpermute_b32 v174, v188, v186 offset:60
	s_waitcnt vmcnt(32) lgkmcnt(3)
	v_pk_fma_f32 v[160:161], v[52:53], v[168:169], v[160:161] op_sel_hi:[1,0,1]
	v_pk_fma_f32 v[162:163], v[54:55], v[168:169], v[162:163] op_sel_hi:[1,0,1]
	global_load_dwordx4 v[52:55], v187, s[64:65] nt
	s_add_u32 s64, s64, 0x2000
	s_addc_u32 s65, s65, 0
	ds_bpermute_b32 v168, v188, v186 offset:64
	s_waitcnt vmcnt(32) lgkmcnt(3)
	v_pk_fma_f32 v[164:165], v[56:57], v[170:171], v[164:165] op_sel_hi:[1,0,1]
	v_pk_fma_f32 v[166:167], v[58:59], v[170:171], v[166:167] op_sel_hi:[1,0,1]
	global_load_dwordx4 v[56:59], v187, s[64:65] nt
	s_add_u32 s64, s64, 0x2000
	s_addc_u32 s65, s65, 0
	ds_bpermute_b32 v170, v188, v186 offset:68
	s_waitcnt vmcnt(32) lgkmcnt(3)
	v_pk_fma_f32 v[160:161], v[60:61], v[172:173], v[160:161] op_sel_hi:[1,0,1]
	v_pk_fma_f32 v[162:163], v[62:63], v[172:173], v[162:163] op_sel_hi:[1,0,1]
	global_load_dwordx4 v[60:63], v187, s[64:65] nt
	s_add_u32 s64, s64, 0x2000
	s_addc_u32 s65, s65, 0
	ds_bpermute_b32 v172, v188, v186 offset:72
	s_waitcnt vmcnt(32) lgkmcnt(3)
	v_pk_fma_f32 v[164:165], v[64:65], v[174:175], v[164:165] op_sel_hi:[1,0,1]
	v_pk_fma_f32 v[166:167], v[66:67], v[174:175], v[166:167] op_sel_hi:[1,0,1]
	global_load_dwordx4 v[64:67], v187, s[64:65] nt
	s_add_u32 s64, s64, 0x2000
	s_addc_u32 s65, s65, 0
	ds_bpermute_b32 v174, v188, v186 offset:76
	s_waitcnt vmcnt(32) lgkmcnt(3)
	v_pk_fma_f32 v[160:161], v[68:69], v[168:169], v[160:161] op_sel_hi:[1,0,1]
	v_pk_fma_f32 v[162:163], v[70:71], v[168:169], v[162:163] op_sel_hi:[1,0,1]
	global_load_dwordx4 v[68:71], v187, s[64:65] nt
	s_add_u32 s64, s64, 0x2000
	s_addc_u32 s65, s65, 0
	ds_bpermute_b32 v168, v188, v186 offset:80
	s_waitcnt vmcnt(32) lgkmcnt(3)
	v_pk_fma_f32 v[164:165], v[72:73], v[170:171], v[164:165] op_sel_hi:[1,0,1]
	v_pk_fma_f32 v[166:167], v[74:75], v[170:171], v[166:167] op_sel_hi:[1,0,1]
	global_load_dwordx4 v[72:75], v187, s[64:65] nt
	s_add_u32 s64, s64, 0x2000
	s_addc_u32 s65, s65, 0
	ds_bpermute_b32 v170, v188, v186 offset:84
	s_waitcnt vmcnt(32) lgkmcnt(3)
; __device__ __forceinline__ void sb_decode_stream(Frame& F, unsigned* qctr, int base, int limit) {
;     ...
;         f32x4 o4 = {0.f, 0.f, 0.f, 0.f};
; #pragma unroll
;         for (int i = 0; i < 16; ++i) { const float aj = __shfl(a, 2 * i + half); o4 += aj * A[i]; }
;         const f32x4 q4n = *(const f32x4*)(SSP(S_PROJ) + (size_t)bn * IN_COLS + hn * HD + 4 * l32);
; #pragma unroll
;         for (int i = 0; i < 16; ++i) A[i] = __builtin_nontemporal_load((const f32x4*)(CK + cbn + (size_t)(2 * i) * stepn));
; #pragma unroll
;         for (int i = 0; i < 16; ++i) { const float aj = __shfl(a, 32 + 2 * i + half); o4 += aj * B[i]; }
; #pragma unroll
;         for (int i = 0; i < 16; ++i) B[i] = __builtin_nontemporal_load((const f32x4*)(CK + cbn + (size_t)(32 + 2 * i) * stepn));
;         o4.x += __shfl_xor(o4.x, 32); o4.y += __shfl_xor(o4.y, 32); o4.z += __shfl_xor(o4.z, 32); o4.w += __shfl_xor(o4.w, 32);
;         float* P = SSP(S_PART) + ((size_t)bh * DSEG + blk) * DPART;
;         if (half == 0) *(f32x4*)(P + 4 * l32) = o4; if (lane == 0) P[128] = tot;
;         if (!more) break;
;         it = itn; cb = cbn; q4 = q4n;
	v_pk_fma_f32 v[160:161], v[76:77], v[172:173], v[160:161] op_sel_hi:[1,0,1]
	v_pk_fma_f32 v[162:163], v[78:79], v[172:173], v[162:163] op_sel_hi:[1,0,1]
	global_load_dwordx4 v[76:79], v187, s[64:65] nt
	s_add_u32 s64, s64, 0x2000
	s_addc_u32 s65, s65, 0
	ds_bpermute_b32 v172, v188, v186 offset:88
	s_waitcnt vmcnt(32) lgkmcnt(3)
	v_pk_fma_f32 v[164:165], v[80:81], v[174:175], v[164:165] op_sel_hi:[1,0,1]
	v_pk_fma_f32 v[166:167], v[82:83], v[174:175], v[166:167] op_sel_hi:[1,0,1]
	global_load_dwordx4 v[80:83], v187, s[64:65] nt
	s_add_u32 s64, s64, 0x2000
	s_addc_u32 s65, s65, 0
	ds_bpermute_b32 v174, v188, v186 offset:92
	s_waitcnt vmcnt(32) lgkmcnt(3)
	v_pk_fma_f32 v[160:161], v[84:85], v[168:169], v[160:161] op_sel_hi:[1,0,1]
	v_pk_fma_f32 v[162:163], v[86:87], v[168:169], v[162:163] op_sel_hi:[1,0,1]
	global_load_dwordx4 v[84:87], v187, s[64:65] nt
	s_add_u32 s64, s64, 0x2000
	s_addc_u32 s65, s65, 0
	ds_bpermute_b32 v168, v188, v186 offset:96
	s_waitcnt vmcnt(32) lgkmcnt(3)
	v_pk_fma_f32 v[164:165], v[88:89], v[170:171], v[164:165] op_sel_hi:[1,0,1]
	v_pk_fma_f32 v[166:167], v[90:91], v[170:171], v[166:167] op_sel_hi:[1,0,1]
	global_load_dwordx4 v[88:91], v187, s[64:65] nt
	s_add_u32 s64, s64, 0x2000
	s_addc_u32 s65, s65, 0
	ds_bpermute_b32 v170, v188, v186 offset:100
	s_waitcnt vmcnt(32) lgkmcnt(3)
	v_pk_fma_f32 v[160:161], v[92:93], v[172:173], v[160:161] op_sel_hi:[1,0,1]
	v_pk_fma_f32 v[162:163], v[94:95], v[172:173], v[162:163] op_sel_hi:[1,0,1]
	global_load_dwordx4 v[92:95], v187, s[64:65] nt
	s_add_u32 s64, s64, 0x2000
	s_addc_u32 s65, s65, 0
	ds_bpermute_b32 v172, v188, v186 offset:104
	s_waitcnt vmcnt(32) lgkmcnt(3)
	v_pk_fma_f32 v[164:165], v[96:97], v[174:175], v[164:165] op_sel_hi:[1,0,1]
	v_pk_fma_f32 v[166:167], v[98:99], v[174:175], v[166:167] op_sel_hi:[1,0,1]
	global_load_dwordx4 v[96:99], v187, s[64:65] nt
	s_add_u32 s64, s64, 0x2000
	s_addc_u32 s65, s65, 0
	ds_bpermute_b32 v174, v188, v186 offset:108
	s_waitcnt vmcnt(32) lgkmcnt(3)
	v_pk_fma_f32 v[160:161], v[100:101], v[168:169], v[160:161] op_sel_hi:[1,0,1]
	v_pk_fma_f32 v[162:163], v[102:103], v[168:169], v[162:163] op_sel_hi:[1,0,1]
	global_load_dwordx4 v[100:103], v187, s[64:65] nt
	s_add_u32 s64, s64, 0x2000
	s_addc_u32 s65, s65, 0
	ds_bpermute_b32 v168, v188, v186 offset:112
	s_waitcnt vmcnt(32) lgkmcnt(3)
	v_pk_fma_f32 v[164:165], v[104:105], v[170:171], v[164:165] op_sel_hi:[1,0,1]
	v_pk_fma_f32 v[166:167], v[106:107], v[170:171], v[166:167] op_sel_hi:[1,0,1]
	global_load_dwordx4 v[104:107], v187, s[64:65] nt
	s_add_u32 s64, s64, 0x2000
	s_addc_u32 s65, s65, 0
	ds_bpermute_b32 v170, v188, v186 offset:116
	s_waitcnt vmcnt(32) lgkmcnt(3)
	v_pk_fma_f32 v[160:161], v[108:109], v[172:173], v[160:161] op_sel_hi:[1,0,1]
	v_pk_fma_f32 v[162:163], v[110:111], v[172:173], v[162:163] op_sel_hi:[1,0,1]
	global_load_dwordx4 v[108:111], v187, s[64:65] nt
	s_add_u32 s64, s64, 0x2000
	s_addc_u32 s65, s65, 0
	ds_bpermute_b32 v172, v188, v186 offset:120
	s_waitcnt vmcnt(32) lgkmcnt(3)
	v_pk_fma_f32 v[164:165], v[112:113], v[174:175], v[164:165] op_sel_hi:[1,0,1]
	v_pk_fma_f32 v[166:167], v[114:115], v[174:175], v[166:167] op_sel_hi:[1,0,1]
	global_load_dwordx4 v[112:115], v187, s[64:65] nt
	s_add_u32 s64, s64, 0x2000
	s_addc_u32 s65, s65, 0
	ds_bpermute_b32 v174, v188, v186 offset:124
	s_waitcnt vmcnt(32) lgkmcnt(3)
	v_pk_fma_f32 v[160:161], v[116:117], v[168:169], v[160:161] op_sel_hi:[1,0,1]
	v_pk_fma_f32 v[162:163], v[118:119], v[168:169], v[162:163] op_sel_hi:[1,0,1]
	global_load_dwordx4 v[116:119], v187, s[64:65] nt
	s_add_u32 s64, s64, 0x2000
	s_addc_u32 s65, s65, 0
	s_waitcnt vmcnt(32) lgkmcnt(2)
	v_pk_fma_f32 v[164:165], v[120:121], v[170:171], v[164:165] op_sel_hi:[1,0,1]
	v_pk_fma_f32 v[166:167], v[122:123], v[170:171], v[166:167] op_sel_hi:[1,0,1]
	global_load_dwordx4 v[120:123], v187, s[64:65] nt
	s_add_u32 s64, s64, 0x2000
	s_addc_u32 s65, s65, 0
	s_waitcnt vmcnt(32) lgkmcnt(1)
	v_pk_fma_f32 v[160:161], v[124:125], v[172:173], v[160:161] op_sel_hi:[1,0,1]
	v_pk_fma_f32 v[162:163], v[126:127], v[172:173], v[162:163] op_sel_hi:[1,0,1]
	global_load_dwordx4 v[124:127], v187, s[64:65] nt
	s_add_u32 s64, s64, 0x2000
	s_addc_u32 s65, s65, 0
	s_waitcnt vmcnt(32) lgkmcnt(0)
	v_pk_fma_f32 v[164:165], v[128:129], v[174:175], v[164:165] op_sel_hi:[1,0,1]
	v_pk_fma_f32 v[166:167], v[130:131], v[174:175], v[166:167] op_sel_hi:[1,0,1]
	global_load_dwordx4 v[128:131], v187, s[64:65] nt
	s_add_u32 s64, s64, 0x2000
	s_addc_u32 s65, s65, 0
	s_nop 1
	v_pk_add_f32 v[160:161], v[160:161], v[164:165]
	v_pk_add_f32 v[162:163], v[162:163], v[166:167]
	s_nop 1
	v_mov_b32_e32 v164, v160
	v_mov_b32_e32 v165, v161
	v_mov_b32_e32 v166, v162
	v_mov_b32_e32 v167, v163
	v_permlane32_swap_b32_e32 v160, v164
	v_permlane32_swap_b32_e32 v161, v165
	v_permlane32_swap_b32_e32 v162, v166
	v_permlane32_swap_b32_e32 v163, v167
	v_pk_add_f32 v[160:161], v[160:161], v[164:165]
	v_pk_add_f32 v[162:163], v[162:163], v[166:167]
	s_nop 1
	s_mov_b32 exec_hi, 0
	global_store_dwordx4 v193, v[160:163], s[70:71]
	s_mov_b32 exec_lo, 1
	global_store_dword v189, v183, s[70:71] offset:512
	s_mov_b64 exec, -1
	s_mov_b32 s72, s73
	s_branch .Ldqc_loop

; __device__ __forceinline__ void sb_decode_stream(Frame& F, unsigned* qctr, int base, int limit) {
;     const float* CK = kin(2); const float* CV = kin(3); const int* PT = (const int*)kin(4);
;     int lane = F.lane; asm volatile("" : "+v"(lane));
;     const int half = lane >> 5, l32 = lane & 31;
;     const float k1 = SB_SCALE * 1.4426950408889634f;
;     const size_t lo = (size_t)half * (NH * HD) + 4 * l32;
;     int it;
;     { const unsigned v = __hip_atomic_fetch_add(qctr, 1u, __ATOMIC_RELAXED, __HIP_MEMORY_SCOPE_AGENT);
;       it = (int)(__builtin_amdgcn_readfirstlane(v) >> 6); if (it >= limit) return; it += base; }
.LBB0_1449:
	s_load_dwordx2 s[50:51], s[0:1], 0x10
	s_load_dwordx2 s[52:53], s[0:1], 0x18
	s_load_dwordx2 s[54:55], s[0:1], 0x20
	s_load_dwordx2 s[56:57], s[0:1], 0x60
	s_add_u32 s58, s26, 0x1100
	s_addc_u32 s59, s27, 0
	s_add_u32 s60, s26, 0x2ff18000
	s_addc_u32 s61, s27, 0
	s_add_u32 s62, s26, 0x2ff70400
	s_addc_u32 s63, s27, 0
	s_mov_b32 s76, 0xcccccccc
	s_mov_b32 s77, 0xcccccccc
	s_mov_b32 s78, 0xaaaaaaaa
	s_mov_b32 s79, 0xaaaaaaaa
	v_and_b32_e32 v193, 31, v199
	v_lshrrev_b32_e32 v188, 5, v199
	v_lshlrev_b32_e32 v193, 4, v193
	v_lshl_add_u32 v187, v188, 12, v193
	v_lshlrev_b32_e32 v188, 7, v188
	v_mov_b32_e32 v189, 0
	v_mov_b32_e32 v190, 64
	v_mov_b32_e32 v190, 0x400
	s_mov_b32 s37, 0x251e0
	s_cmp_eq_u32 s94, 0
	s_cbranch_scc0 .Ldqd_pro
	s_mov_b64 exec, 1
	global_atomic_add v191, v189, v190, s[58:59] sc0
	s_mov_b64 exec, -1
